# attention: exact vmcnt waits and 4-buffer P.V LDS pipelining; phase-4 reorder; GLA loop rewrite
# speedup vs baseline: 1.0145x; 1.0145x over previous
; #define RUN_PH(ph) if ((ph) == ONLY_PH && P.ph_lo <= (ph) && (ph) < P.ph_hi)
; #define RUN_PH(ph) if (P.ph_lo <= (ph) && (ph) < P.ph_hi)
; __global__ void __launch_bounds__(512, 2) mega(Params P) {
;     ...
;     RUN_PH(4) {
;         float gq = fmaxf(fabsf(P.in[11][threadIdx.x & 63]), fabsf(P.in[11][64 + (threadIdx.x & 63)])), gk = fmaxf(fabsf(P.in[12][threadIdx.x & 63]), fabsf(P.in[12][64 + (threadIdx.x & 63)]));
; #pragma unroll
;         for (int o = 1; o < 64; o <<= 1) { gq = fmaxf(gq, __shfl_xor(gq, o)); gk = fmaxf(gk, __shfl_xor(gk, o)); }
;         const float mfix2 = 11.313708498984761f * gq * gk * LOG2E;
;         for (int it = blockIdx.x; it < 512; it += gridDim.x) attn_item(P, it, lds, mfix2);
.LBB0_531:
	s_add_u32 s36, s50, 0xb418000
	s_addc_u32 s37, s51, 0
	s_add_u32 s38, s50, 0x17c18000
	s_addc_u32 s39, s51, 0
	s_cmp_lt_i32 s24, 5
	s_cselect_b64 s[42:43], -1, 0
	s_and_b64 s[0:1], s[42:43], s[0:1]
	s_andn2_b64 vcc, exec, s[0:1]
	s_cbranch_vccnz .LBB0_571
	s_mov_b32 s82, 0
	s_bitcmp1_b32 s22, 7
	s_cbranch_scc0 .Lp4_att
	s_mov_b32 s82, 1
	s_branch .LBB0_553

; #define LAS __attribute__((address_space(3)))
; #define ATT_LOAD(i, kr, vr) do { const int _p = ATT_POS0(i); \
;         kr[0] = *(const u32x4*)(Kb + (size_t)(_p + kkey0) * 128 + kseg * 8); kr[1] = *(const u32x4*)(Kb + (size_t)(_p + kkey0 + 32) * 128 + kseg * 8); \
;         vr[0] = *(const u32x4*)(Vtb + (size_t)vdim0 * KVLEN + _p + vseg * 8); vr[1] = *(const u32x4*)(Vtb + (size_t)(vdim0 + 64) * KVLEN + _p + vseg * 8); } while (0)
; __device__ __forceinline__ void attn_item(const Params& P, int item, LAS unsigned char* lds, float mfix2) {
;     const int tid = threadIdx.x, lane = tid & 63, wave = __builtin_amdgcn_readfirstlane(tid >> 6), r16 = lane & 15, q4 = lane >> 4;
;     const int hp = item & 1, qb = (item >> 1) & 15, kvh = (item >> 5) & 1, b = item >> 6;
;     const int head = kvh * 4 + hp * 2 + (wave >> 2), rw0 = (wave & 3) * 32, q0 = qb * 128;
;     const bf16_t* Kb = (const bf16_t*)(P.ws + WS_KP) + (size_t)(b * 2 + kvh) * KVLEN * 128;
;     const bf16_t* Vtb = (const bf16_t*)(P.ws + WS_VTA) + (size_t)(b * 2 + kvh) * 128 * KVLEN;
;     bf16_t* mix = (bf16_t*)(P.ws + WS_MIX);
;     LAS unsigned char* Pw = lds + 71680 + wave * 4608;
;     bf16x8 qf[2][4];
;     { const bf16_t* qbase = (const bf16_t*)(P.ws + WS_QP) + ((size_t)(b * 8 + head) * SEQ + q0 + rw0) * 128;
; #pragma unroll
;       for (int rb = 0; rb < 2; ++rb)
; #pragma unroll
;           for (int ks = 0; ks < 4; ++ks) qf[rb][ks] = *(const bf16x8*)(qbase + (rb * 16 + r16) * 128 + ks * 32 + q4 * 8); }
;     const float psink = exp2f(P.in[13][head] * LOG2E - mfix2);
;     f32x4 o[2][8]; float lsum[2][4];
; #pragma unroll
;     for (int rb = 0; rb < 2; ++rb) {
; #pragma unroll
;         for (int db = 0; db < 8; ++db) o[rb][db] = (f32x4){0.f, 0.f, 0.f, 0.f};
; #pragma unroll
;         for (int j = 0; j < 4; ++j) lsum[rb][j] = 0.f; }
;     const int lt_first = qb == 0 ? 0 : (qb - 1) * 2, lt_last = (qb * 2 + 3) > 31 ? 31 : (qb * 2 + 3), ntiles = 4 + lt_last - lt_first + 1;
;     const int kkey0 = tid >> 4, kseg = tid & 15, vdim0 = tid >> 3, vseg = tid & 7;
;     u32x4 krA[2], vrA[2], krB[2], vrB[2];
;     ...
;     ATT_LOAD(0, krA, vrA); ATT_STORE(0, krA, vrA);
;     ATT_LOAD(1, krA, vrA);
;     __syncthreads();
.LBB0_536:
	s_bfe_u32 s5, s29, 0x10005
	s_lshl_b32 s7, s29, 1
	v_readfirstlane_b32 s4, v224
	s_lshl_b32 s6, s5, 2
	s_and_b32 s7, s7, 2
	s_lshr_b32 s54, s4, 6
	s_ashr_i32 s0, s29, 6
	s_or_b32 s33, s6, s7
	s_lshr_b32 s6, s4, 8
	s_lshr_b32 s4, s4, 1
	s_and_b32 s44, s4, 0x60
	s_lshl_b32 s4, s0, 1
	s_add_i32 s33, s33, s6
	s_or_b32 s6, s4, s5
	s_lshl_b32 s4, s0, 3
	s_add_i32 s4, s33, s4
	s_bfe_u32 s8, s29, 0x40001
	s_ashr_i32 s5, s4, 31
	s_lshl_b32 s45, s8, 7
	s_lshl_b64 s[4:5], s[4:5], 11
	s_or_b32 s4, s4, s45
	s_or_b32 s4, s4, s44
	s_lshl_b64 s[4:5], s[4:5], 8
	v_lshl_add_u64 v[16:17], v[158:159], 0, s[4:5]
	s_mul_i32 s9, s6, 0x90000
	v_add_co_u32_e32 v0, vcc, s17, v16
	s_lshl_b32 s4, s33, 2
	s_mul_hi_i32 s7, s6, 0x90000
	global_load_dwordx4 v[40:43], v[16:17], off offset:64
	global_load_dwordx4 v[44:47], v[16:17], off offset:128
	v_addc_co_u32_e32 v1, vcc, 0, v17, vcc
	global_load_dwordx4 v[48:51], v[16:17], off offset:192
	global_load_dwordx4 v[52:55], v[0:1], off
	global_load_dwordx4 v[56:59], v[0:1], off offset:64
	global_load_dwordx4 v[60:63], v[0:1], off offset:128
	global_load_dwordx4 v[64:67], v[0:1], off offset:192
	v_mov_b32_e32 v0, s4
	s_add_u32 s4, s15, s9
	s_addc_u32 s5, s16, s7
	v_mad_i64_i32 v[8:9], s[6:7], s6, v202, v[164:165]
	v_mov_b32_e32 v171, v157
	v_mov_b32_e32 v167, v157
	v_lshl_add_u64 v[172:173], v[8:9], 0, v[170:171]
	global_load_dword v208, v0, s[78:79]
	v_lshl_add_u64 v[0:1], s[4:5], 0, v[166:167]
	v_add_co_u32_e32 v12, vcc, s18, v172
	v_lshl_add_u64 v[18:19], v[0:1], 0, v[156:157]
	v_mov_b32_e32 v169, v157
	v_addc_co_u32_e32 v13, vcc, 0, v173, vcc
	v_lshl_add_u64 v[0:1], s[4:5], 0, v[168:169]
	v_add_co_u32_e32 v20, vcc, 0x4000, v18
	v_lshl_add_u64 v[4:5], v[0:1], 0, v[156:157]
	s_nop 0
	v_addc_co_u32_e32 v21, vcc, 0, v19, vcc
	global_load_dwordx4 v[0:3], v[18:19], off
	s_nop 0
	global_load_dwordx4 v[4:7], v[4:5], off
	v_add_co_u32_e32 v18, vcc, 0x6000, v18
	global_load_dwordx4 v[8:11], v[172:173], off
	v_lshl_add_u64 v[174:175], v[172:173], 0, s[2:3]
	global_load_dwordx4 v[12:15], v[12:13], off
	s_nop 0
	global_load_dwordx4 v[84:87], v[20:21], off
	v_addc_co_u32_e32 v19, vcc, 0, v19, vcc
	global_load_dwordx4 v[96:99], v[172:173], off offset:128
	global_load_dwordx4 v[76:79], v[16:17], off
	global_load_dwordx4 v[100:103], v[174:175], off offset:128
	global_load_dwordx4 v[88:91], v[18:19], off
	s_lshl_b32 s55, s8, 1
	s_add_i32 s6, s55, -2
	s_cmp_lg_u32 s8, 0
	s_cselect_b32 s56, s6, 0
	s_add_i32 s6, s55, 7
	s_cmp_lg_u32 s8, 15
	s_cselect_b32 s6, s6, 35
	s_sub_i32 s57, s6, s56
	s_cmp_lt_i32 s57, 0
	s_waitcnt vmcnt(8)
	ds_write_b128 v203, v[0:3]
	s_waitcnt vmcnt(7)
	ds_write_b128 v203, v[4:7] offset:8704
	s_waitcnt vmcnt(6)
	ds_write_b128 v204, v[8:11] offset:34816
	s_waitcnt vmcnt(5)
	ds_write_b128 v204, v[12:15] offset:44032
	s_waitcnt lgkmcnt(0)
	s_barrier
	s_cbranch_scc1 .LBB0_534
	v_lshl_add_u64 v[176:177], s[4:5], 0, v[156:157]
	s_mul_i32 s4, s54, 0x1200
	s_add_i32 s4, s4, 0
	s_add_i32 s4, s4, 0x11800
	s_or_b32 s5, s44, s45
	v_add_u32_e32 v0, s4, v188
	v_mov_b32_e32 v92, v157
	v_mov_b32_e32 v93, v157
	v_mov_b32_e32 v94, v157
	v_mov_b32_e32 v95, v157
	v_add_u32_e32 v167, s5, v189
	v_add_u32_e32 v169, s4, v186
	s_lshl_b32 s4, s56, 6
	v_add_u32_e32 v209, v0, v190
	v_mov_b64_e32 v[24:25], v[92:93]
	v_mov_b64_e32 v[20:21], v[92:93]
	v_mov_b64_e32 v[16:17], v[92:93]
	v_mov_b64_e32 v[12:13], v[92:93]
	v_mov_b64_e32 v[8:9], v[92:93]
	v_mov_b64_e32 v[4:5], v[92:93]
	v_mov_b64_e32 v[0:1], v[92:93]
	v_mov_b64_e32 v[126:127], v[94:95]
	v_mov_b64_e32 v[106:107], v[94:95]
	v_mov_b64_e32 v[80:81], v[92:93]
	v_mov_b64_e32 v[72:73], v[92:93]
	v_mov_b64_e32 v[68:69], v[92:93]
	v_mov_b64_e32 v[36:37], v[92:93]
	v_mov_b64_e32 v[32:33], v[92:93]
	v_mov_b64_e32 v[28:29], v[92:93]
	s_or_b32 s58, s55, 1
	s_add_i32 s59, s5, 0x41
	s_add_i32 s60, s5, 0x19f
	v_add_u32_e32 v171, 16, v167
	s_add_i32 s61, s4, 0xc0
	v_mov_b32_e32 v210, 0
	s_mov_b32 s62, 3
	v_mov_b64_e32 v[26:27], v[94:95]
	v_mov_b64_e32 v[22:23], v[94:95]
	v_mov_b64_e32 v[18:19], v[94:95]
	v_mov_b64_e32 v[14:15], v[94:95]
	v_mov_b64_e32 v[10:11], v[94:95]
	v_mov_b64_e32 v[6:7], v[94:95]
	v_mov_b64_e32 v[2:3], v[94:95]
	v_mov_b64_e32 v[124:125], v[92:93]
	v_mov_b64_e32 v[104:105], v[92:93]
	v_mov_b64_e32 v[82:83], v[94:95]
	v_mov_b64_e32 v[74:75], v[94:95]
	v_mov_b64_e32 v[70:71], v[94:95]
	v_mov_b64_e32 v[38:39], v[94:95]
	v_mov_b64_e32 v[34:35], v[94:95]
	v_mov_b64_e32 v[30:31], v[94:95]
	v_mov_b32_e32 v211, 0
	v_mov_b32_e32 v212, 0
	v_mov_b32_e32 v213, 0
	v_mov_b32_e32 v214, 0
	v_mov_b32_e32 v215, 0
	v_mov_b32_e32 v216, 0
	v_mov_b32_e32 v217, 0
	s_waitcnt vmcnt(2)
	s_branch .LBB0_539

; #define LAS __attribute__((address_space(3)))
; __device__ __forceinline__ bf16_t f2bf1(float x) { return (bf16_t)(cvt_pk_bf16(x, 0.f) & 0xffffu); }
; #define MFMA16(a, b, c) __builtin_amdgcn_mfma_f32_16x16x32_bf16((a), (b), (c), 0, 0, 0)
; __device__ __forceinline__ void attn_item(const Params& P, int item, LAS unsigned char* lds, float mfix2) {
;     ...
;         if (live) {
;         f32x4 s[2][4];
; #pragma unroll
;         for (int rb = 0; rb < 2; ++rb)
; #pragma unroll
;             for (int cb = 0; cb < 4; ++cb) s[rb][cb] = (f32x4){0.f, 0.f, 0.f, 0.f};
; #pragma unroll
;         for (int ks = 0; ks < 4; ++ks)
; #pragma unroll
;             for (int cb = 0; cb < 4; ++cb) { const bf16x8 kf = *(const LAS bf16x8*)(kbuf + (cb * 16 + r16) * 272 + ks * 64 + q4 * 16);
; #pragma unroll
;                 for (int rb = 0; rb < 2; ++rb) s[rb][cb] = MFMA16(qf[rb][ks], kf, s[rb][cb]); }
; #pragma unroll
;         for (int rb = 0; rb < 2; ++rb)
; #pragma unroll
;             for (int cb = 0; cb < 4; ++cb)
; #pragma unroll
;                 for (int j = 0; j < 4; ++j) {
;                     float p = exp2f(s[rb][cb][j] - mfix2);
;                     if (masked) { const int dq = (q0 + rw0 + rb * 16 + q4 * 4 + j) - (p0 - CTXL + cb * 16 + r16); if (dq > 128 || dq < -128) p = 0.f; }
;                     lsum[rb][j] += p;
;                     *(LAS bf16_t*)(Pw + (rb * 16 + q4 * 4 + j) * 144 + (cb * 16 + r16) * 2) = f2bf1(p);
;                 }
.LBB0_543:
	s_andn2_b64 vcc, exec, s[12:13]
	s_cbranch_vccnz .LBB0_545
	ds_read_b128 v[128:131], v205
	ds_read_b128 v[226:229], v205 offset:64
	ds_read_b128 v[136:139], v205 offset:4352
	ds_read_b128 v[144:147], v205 offset:8704
	ds_read_b128 v[152:155], v205 offset:13056
	s_waitcnt lgkmcnt(4)
	v_mfma_f32_16x16x32_bf16 v[132:135], v[76:79], v[128:131], 0
	s_sub_i32 s12, 0x100, s21
	s_sub_i32 s13, 0xf0, s21
	v_mfma_f32_16x16x32_bf16 v[128:131], v[52:55], v[128:131], 0
	s_waitcnt lgkmcnt(3)
	v_mfma_f32_16x16x32_bf16 v[132:135], v[40:43], v[226:229], v[132:135]
	v_mfma_f32_16x16x32_bf16 v[128:131], v[56:59], v[226:229], v[128:131]
	ds_read_b128 v[226:229], v205 offset:4416
	s_waitcnt lgkmcnt(3)
	v_mfma_f32_16x16x32_bf16 v[140:143], v[76:79], v[136:139], 0
	v_mfma_f32_16x16x32_bf16 v[136:139], v[52:55], v[136:139], 0
	s_waitcnt lgkmcnt(0)
	v_mfma_f32_16x16x32_bf16 v[140:143], v[40:43], v[226:229], v[140:143]
	v_mfma_f32_16x16x32_bf16 v[136:139], v[56:59], v[226:229], v[136:139]
	ds_read_b128 v[226:229], v205 offset:8768
	v_mfma_f32_16x16x32_bf16 v[148:151], v[76:79], v[144:147], 0
	v_mfma_f32_16x16x32_bf16 v[144:147], v[52:55], v[144:147], 0
	s_waitcnt lgkmcnt(0)
	v_mfma_f32_16x16x32_bf16 v[148:151], v[40:43], v[226:229], v[148:151]
	v_mfma_f32_16x16x32_bf16 v[144:147], v[56:59], v[226:229], v[144:147]
	ds_read_b128 v[226:229], v205 offset:13120
	v_mfma_f32_16x16x32_bf16 v[218:221], v[76:79], v[152:155], 0
	v_mfma_f32_16x16x32_bf16 v[152:155], v[52:55], v[152:155], 0
	s_waitcnt lgkmcnt(0)
	v_mfma_f32_16x16x32_bf16 v[218:221], v[40:43], v[226:229], v[218:221]
	v_mfma_f32_16x16x32_bf16 v[152:155], v[56:59], v[226:229], v[152:155]
	ds_read_b128 v[226:229], v205 offset:128
	s_waitcnt lgkmcnt(0)
	v_mfma_f32_16x16x32_bf16 v[132:135], v[44:47], v[226:229], v[132:135]
	v_mfma_f32_16x16x32_bf16 v[128:131], v[60:63], v[226:229], v[128:131]
	ds_read_b128 v[226:229], v205 offset:4480
	s_waitcnt lgkmcnt(0)
	v_mfma_f32_16x16x32_bf16 v[230:233], v[44:47], v[226:229], v[140:143]
	s_nop 2
	ds_read_b128 v[140:143], v205 offset:8832
	s_waitcnt lgkmcnt(0)
	v_mfma_f32_16x16x32_bf16 v[148:151], v[44:47], v[140:143], v[148:151]
	v_mfma_f32_16x16x32_bf16 v[144:147], v[60:63], v[140:143], v[144:147]
	ds_read_b128 v[140:143], v205 offset:13184
	v_mfma_f32_16x16x32_bf16 v[136:139], v[60:63], v[226:229], v[136:139]
	s_waitcnt lgkmcnt(0)
	v_mfma_f32_16x16x32_bf16 v[218:221], v[44:47], v[140:143], v[218:221]
	v_mfma_f32_16x16x32_bf16 v[226:229], v[60:63], v[140:143], v[152:155]
	ds_read_b128 v[140:143], v205 offset:192
	s_waitcnt lgkmcnt(0)
	v_mfma_f32_16x16x32_bf16 v[234:237], v[48:51], v[140:143], v[132:135]
	v_mfma_f32_16x16x32_bf16 v[140:143], v[64:67], v[140:143], v[128:131]
	s_nop 2
	ds_read_b128 v[128:131], v205 offset:4544
	s_waitcnt lgkmcnt(0)
	v_mfma_f32_16x16x32_bf16 v[152:155], v[48:51], v[128:131], v[230:233]
	s_nop 1
	v_sub_f32_e32 v140, v140, v183
	s_nop 4
	v_sub_f32_e32 v152, v152, v183
	v_mfma_f32_16x16x32_bf16 v[136:139], v[64:67], v[128:131], v[136:139]
	ds_read_b128 v[128:131], v205 offset:8896
	s_waitcnt lgkmcnt(0)
	v_mfma_f32_16x16x32_bf16 v[148:151], v[48:51], v[128:131], v[148:151]
	s_nop 4
	v_sub_f32_e32 v136, v136, v183
	v_mfma_f32_16x16x32_bf16 v[132:135], v[64:67], v[128:131], v[144:147]
	ds_read_b128 v[128:131], v205 offset:13248
	v_sub_f32_e32 v148, v148, v183
	s_waitcnt lgkmcnt(0)
	v_mfma_f32_16x16x32_bf16 v[144:147], v[48:51], v[128:131], v[218:221]
	s_nop 2
	v_sub_f32_e32 v219, v234, v183
	v_cmp_gt_f32_e32 vcc, s19, v219
	v_add_u32_e32 v218, s12, v167
	s_nop 1
	v_sub_f32_e32 v144, v144, v183
	v_cndmask_b32_e32 v220, 0, v206, vcc
	v_add_f32_e32 v219, v219, v220
	v_exp_f32_e32 v219, v219
	v_cndmask_b32_e32 v220, 0, v207, vcc
	v_cmp_gt_u32_e32 vcc, s28, v218
	s_and_b64 s[30:31], s[10:11], vcc
	v_ldexp_f32 v219, v219, v220
	v_cndmask_b32_e64 v219, v219, 0, s[30:31]
	v_add_f32_e32 v217, v217, v219
	v_cvt_pk_bf16_f32 v219, v219, s0
	ds_write_b16 v209, v219
	v_sub_f32_e32 v219, v235, v183
	v_cmp_gt_f32_e32 vcc, s19, v219
	v_sub_f32_e32 v132, v132, v183
	v_mfma_f32_16x16x32_bf16 v[128:131], v[64:67], v[128:131], v[226:229]
	v_cndmask_b32_e32 v220, 0, v206, vcc
	v_add_f32_e32 v219, v219, v220
	v_exp_f32_e32 v219, v219
	v_cndmask_b32_e32 v220, 0, v207, vcc
	v_ldexp_f32 v219, v219, v220
	v_add_u32_e32 v220, 1, v218
	v_cmp_gt_u32_e32 vcc, s28, v220
	s_and_b64 s[30:31], s[10:11], vcc
	v_cndmask_b32_e64 v219, v219, 0, s[30:31]
	v_add_f32_e32 v216, v216, v219
	v_cvt_pk_bf16_f32 v219, v219, s0
	ds_write_b16 v209, v219 offset:144
	v_sub_f32_e32 v219, v236, v183
	v_cmp_gt_f32_e32 vcc, s19, v219
	v_sub_f32_e32 v128, v128, v183
	s_nop 0
	v_cndmask_b32_e32 v220, 0, v206, vcc
	v_add_f32_e32 v219, v219, v220
	v_exp_f32_e32 v219, v219
	v_cndmask_b32_e32 v220, 0, v207, vcc
	v_ldexp_f32 v219, v219, v220
	v_add_u32_e32 v220, 2, v218
	v_cmp_gt_u32_e32 vcc, s28, v220
	s_and_b64 s[30:31], s[10:11], vcc
	v_cndmask_b32_e64 v219, v219, 0, s[30:31]
	v_add_f32_e32 v215, v215, v219
	v_cvt_pk_bf16_f32 v219, v219, s0
	ds_write_b16 v209, v219 offset:288
	v_sub_f32_e32 v219, v237, v183
	v_cmp_gt_f32_e32 vcc, s19, v219
	v_add_u32_e32 v218, 3, v218
	s_nop 0
	v_cndmask_b32_e32 v220, 0, v206, vcc
	v_add_f32_e32 v219, v219, v220
	v_exp_f32_e32 v219, v219
	v_cndmask_b32_e32 v220, 0, v207, vcc
	v_cmp_gt_u32_e32 vcc, s28, v218
	s_and_b64 s[30:31], s[10:11], vcc
	v_ldexp_f32 v219, v219, v220
	v_cmp_gt_f32_e32 vcc, s19, v152
	v_cndmask_b32_e64 v218, v219, 0, s[30:31]
	v_add_f32_e32 v214, v214, v218
	v_cndmask_b32_e32 v219, 0, v206, vcc
	v_add_f32_e32 v152, v152, v219
	v_exp_f32_e32 v152, v152
	v_cvt_pk_bf16_f32 v218, v218, s0
	ds_write_b16 v209, v218 offset:432
	v_add_u32_e32 v218, s13, v167
; #define LAS __attribute__((address_space(3)))
; __device__ __forceinline__ bf16_t f2bf1(float x) { return (bf16_t)(cvt_pk_bf16(x, 0.f) & 0xffffu); }
; __device__ __forceinline__ void attn_item(const Params& P, int item, LAS unsigned char* lds, float mfix2) {
;     ...
;         for (int rb = 0; rb < 2; ++rb)
; #pragma unroll
;             for (int cb = 0; cb < 4; ++cb)
; #pragma unroll
;                 for (int j = 0; j < 4; ++j) {
;                     float p = exp2f(s[rb][cb][j] - mfix2);
;                     if (masked) { const int dq = (q0 + rw0 + rb * 16 + q4 * 4 + j) - (p0 - CTXL + cb * 16 + r16); if (dq > 128 || dq < -128) p = 0.f; }
;                     lsum[rb][j] += p;
;                     *(LAS bf16_t*)(Pw + (rb * 16 + q4 * 4 + j) * 144 + (cb * 16 + r16) * 2) = f2bf1(p);
;                 }
	v_cndmask_b32_e32 v219, 0, v207, vcc
	v_cmp_gt_u32_e32 vcc, s28, v218
	v_ldexp_f32 v152, v152, v219
	s_and_b64 s[30:31], s[10:11], vcc
	v_cndmask_b32_e64 v152, v152, 0, s[30:31]
	v_add_f32_e32 v217, v217, v152
	v_cvt_pk_bf16_f32 v152, v152, s0
	ds_write_b16 v209, v152 offset:32
	v_sub_f32_e32 v152, v153, v183
	v_cmp_gt_f32_e32 vcc, s19, v152
	s_nop 1
	v_cndmask_b32_e32 v153, 0, v206, vcc
	v_add_f32_e32 v152, v152, v153
	v_exp_f32_e32 v152, v152
	v_cndmask_b32_e32 v153, 0, v207, vcc
	v_ldexp_f32 v152, v152, v153
	v_add_u32_e32 v153, 1, v218
	v_cmp_gt_u32_e32 vcc, s28, v153
	s_and_b64 s[30:31], s[10:11], vcc
	v_cndmask_b32_e64 v152, v152, 0, s[30:31]
	v_add_f32_e32 v153, v216, v152
	v_cvt_pk_bf16_f32 v152, v152, s0
	ds_write_b16 v209, v152 offset:176
	v_sub_f32_e32 v152, v154, v183
	v_cmp_gt_f32_e32 vcc, s19, v152
	s_nop 1
	v_cndmask_b32_e32 v154, 0, v206, vcc
	v_add_f32_e32 v152, v152, v154
	v_exp_f32_e32 v152, v152
	v_cndmask_b32_e32 v154, 0, v207, vcc
	v_ldexp_f32 v152, v152, v154
	v_add_u32_e32 v154, 2, v218
	v_cmp_gt_u32_e32 vcc, s28, v154
	s_and_b64 s[30:31], s[10:11], vcc
	v_cndmask_b32_e64 v152, v152, 0, s[30:31]
	v_add_f32_e32 v154, v215, v152
	v_cvt_pk_bf16_f32 v152, v152, s0
	ds_write_b16 v209, v152 offset:320
	v_sub_f32_e32 v152, v155, v183
	v_cmp_gt_f32_e32 vcc, s19, v152
	s_nop 1
	v_cndmask_b32_e32 v155, 0, v206, vcc
	v_add_f32_e32 v152, v152, v155
	v_exp_f32_e32 v152, v152
	v_cndmask_b32_e32 v155, 0, v207, vcc
	v_ldexp_f32 v152, v152, v155
	v_add_u32_e32 v155, 3, v218
	v_cmp_gt_u32_e32 vcc, s28, v155
	s_and_b64 s[30:31], s[10:11], vcc
	v_cndmask_b32_e64 v152, v152, 0, s[30:31]
	v_cmp_gt_f32_e32 vcc, s19, v148
	v_add_f32_e32 v155, v214, v152
	v_cvt_pk_bf16_f32 v152, v152, s0
	v_cndmask_b32_e32 v214, 0, v206, vcc
	v_add_f32_e32 v148, v148, v214
	v_exp_f32_e32 v148, v148
	s_sub_i32 s30, 0xe0, s21
	ds_write_b16 v209, v152 offset:464
	v_add_u32_e32 v152, s30, v167
	v_cndmask_b32_e32 v214, 0, v207, vcc
	v_cmp_gt_u32_e32 vcc, s28, v152
	v_ldexp_f32 v148, v148, v214
	s_and_b64 s[68:69], s[10:11], vcc
	v_cndmask_b32_e64 v148, v148, 0, s[68:69]
	v_add_f32_e32 v214, v217, v148
	v_cvt_pk_bf16_f32 v148, v148, s0
	ds_write_b16 v209, v148 offset:64
	v_sub_f32_e32 v148, v149, v183
	v_cmp_gt_f32_e32 vcc, s19, v148
	s_sub_i32 s21, 0xd0, s21
	s_nop 0
	v_cndmask_b32_e32 v149, 0, v206, vcc
	v_add_f32_e32 v148, v148, v149
	v_exp_f32_e32 v148, v148
	v_cndmask_b32_e32 v149, 0, v207, vcc
	v_ldexp_f32 v148, v148, v149
	v_add_u32_e32 v149, 1, v152
	v_cmp_gt_u32_e32 vcc, s28, v149
	s_and_b64 s[68:69], s[10:11], vcc
	v_cndmask_b32_e64 v148, v148, 0, s[68:69]
	v_add_f32_e32 v149, v153, v148
	v_cvt_pk_bf16_f32 v148, v148, s0
	ds_write_b16 v209, v148 offset:208
	v_sub_f32_e32 v148, v150, v183
	v_cmp_gt_f32_e32 vcc, s19, v148
	s_nop 1
	v_cndmask_b32_e32 v150, 0, v206, vcc
	v_add_f32_e32 v148, v148, v150
	v_exp_f32_e32 v148, v148
	v_cndmask_b32_e32 v150, 0, v207, vcc
	v_ldexp_f32 v148, v148, v150
	v_add_u32_e32 v150, 2, v152
	v_cmp_gt_u32_e32 vcc, s28, v150
	s_and_b64 s[68:69], s[10:11], vcc
	v_cndmask_b32_e64 v148, v148, 0, s[68:69]
	v_add_f32_e32 v150, v154, v148
	v_cvt_pk_bf16_f32 v148, v148, s0
	ds_write_b16 v209, v148 offset:352
	v_sub_f32_e32 v148, v151, v183
	v_cmp_gt_f32_e32 vcc, s19, v148
	s_nop 1
	v_cndmask_b32_e32 v151, 0, v206, vcc
	v_add_f32_e32 v148, v148, v151
	v_exp_f32_e32 v148, v148
	v_cndmask_b32_e32 v151, 0, v207, vcc
	v_ldexp_f32 v148, v148, v151
	v_add_u32_e32 v151, 3, v152
	v_cmp_gt_u32_e32 vcc, s28, v151
	s_and_b64 s[68:69], s[10:11], vcc
	v_cmp_gt_f32_e32 vcc, s19, v144
	v_cndmask_b32_e64 v148, v148, 0, s[68:69]
	v_add_f32_e32 v151, v155, v148
	v_cndmask_b32_e32 v152, 0, v206, vcc
	v_add_f32_e32 v144, v144, v152
	v_exp_f32_e32 v144, v144
	v_cvt_pk_bf16_f32 v148, v148, s0
	ds_write_b16 v209, v148 offset:496
	v_add_u32_e32 v148, s21, v167
	v_cndmask_b32_e32 v152, 0, v207, vcc
	v_cmp_gt_u32_e32 vcc, s28, v148
	v_ldexp_f32 v144, v144, v152
	s_and_b64 s[68:69], s[10:11], vcc
	v_cndmask_b32_e64 v144, v144, 0, s[68:69]
	v_add_f32_e32 v217, v214, v144
	v_cvt_pk_bf16_f32 v144, v144, s0
	ds_write_b16 v209, v144 offset:96
	v_sub_f32_e32 v144, v145, v183
	v_cmp_gt_f32_e32 vcc, s19, v144
	s_nop 1
	v_cndmask_b32_e32 v145, 0, v206, vcc
	v_add_f32_e32 v144, v144, v145
	v_exp_f32_e32 v144, v144
	v_cndmask_b32_e32 v145, 0, v207, vcc
	v_ldexp_f32 v144, v144, v145
	v_add_u32_e32 v145, 1, v148
	v_cmp_gt_u32_e32 vcc, s28, v145
	s_and_b64 s[68:69], s[10:11], vcc
	v_cndmask_b32_e64 v144, v144, 0, s[68:69]
	v_add_f32_e32 v216, v149, v144
	v_cvt_pk_bf16_f32 v144, v144, s0
	ds_write_b16 v209, v144 offset:240
	v_sub_f32_e32 v144, v146, v183
	v_cmp_gt_f32_e32 vcc, s19, v144
	s_nop 1
	v_cndmask_b32_e32 v145, 0, v206, vcc
	v_add_f32_e32 v144, v144, v145
	v_exp_f32_e32 v144, v144
	v_cndmask_b32_e32 v145, 0, v207, vcc
	v_ldexp_f32 v144, v144, v145
	v_add_u32_e32 v145, 2, v148
	v_cmp_gt_u32_e32 vcc, s28, v145
	s_and_b64 s[68:69], s[10:11], vcc
	v_cndmask_b32_e64 v144, v144, 0, s[68:69]
	v_add_f32_e32 v215, v150, v144
	v_cvt_pk_bf16_f32 v144, v144, s0
	ds_write_b16 v209, v144 offset:384
	v_sub_f32_e32 v144, v147, v183
	v_cmp_gt_f32_e32 vcc, s19, v144
	s_nop 1
	v_cndmask_b32_e32 v145, 0, v206, vcc
	v_add_f32_e32 v144, v144, v145
	v_exp_f32_e32 v144, v144
	v_cndmask_b32_e32 v145, 0, v207, vcc
	v_ldexp_f32 v144, v144, v145
	v_add_u32_e32 v145, 3, v148
	v_cmp_gt_u32_e32 vcc, s28, v145
	s_and_b64 s[68:69], s[10:11], vcc
	v_cmp_gt_f32_e32 vcc, s19, v140
	v_cndmask_b32_e64 v144, v144, 0, s[68:69]
	v_add_f32_e32 v214, v151, v144
	v_cndmask_b32_e32 v145, 0, v206, vcc
	v_add_f32_e32 v140, v140, v145
	v_exp_f32_e32 v140, v140
	v_cvt_pk_bf16_f32 v144, v144, s0
; #define LAS __attribute__((address_space(3)))
; __device__ __forceinline__ bf16_t f2bf1(float x) { return (bf16_t)(cvt_pk_bf16(x, 0.f) & 0xffffu); }
; __device__ __forceinline__ void attn_item(const Params& P, int item, LAS unsigned char* lds, float mfix2) {
;     ...
;         for (int rb = 0; rb < 2; ++rb)
; #pragma unroll
;             for (int cb = 0; cb < 4; ++cb)
; #pragma unroll
;                 for (int j = 0; j < 4; ++j) {
;                     float p = exp2f(s[rb][cb][j] - mfix2);
;                     if (masked) { const int dq = (q0 + rw0 + rb * 16 + q4 * 4 + j) - (p0 - CTXL + cb * 16 + r16); if (dq > 128 || dq < -128) p = 0.f; }
;                     lsum[rb][j] += p;
;                     *(LAS bf16_t*)(Pw + (rb * 16 + q4 * 4 + j) * 144 + (cb * 16 + r16) * 2) = f2bf1(p);
;                 }
	ds_write_b16 v209, v144 offset:528
	v_add_u32_e32 v144, s12, v171
	v_cndmask_b32_e32 v145, 0, v207, vcc
	v_cmp_gt_u32_e32 vcc, s28, v144
	v_ldexp_f32 v140, v140, v145
	s_and_b64 s[68:69], s[10:11], vcc
	v_cndmask_b32_e64 v140, v140, 0, s[68:69]
	v_add_f32_e32 v145, v213, v140
	v_cvt_pk_bf16_f32 v140, v140, s0
	ds_write_b16 v209, v140 offset:2304
	v_sub_f32_e32 v140, v141, v183
	v_cmp_gt_f32_e32 vcc, s19, v140
	s_nop 1
	v_cndmask_b32_e32 v141, 0, v206, vcc
	v_add_f32_e32 v140, v140, v141
	v_exp_f32_e32 v140, v140
	v_cndmask_b32_e32 v141, 0, v207, vcc
	v_ldexp_f32 v140, v140, v141
	v_add_u32_e32 v141, 1, v144
	v_cmp_gt_u32_e32 vcc, s28, v141
	s_and_b64 s[68:69], s[10:11], vcc
	v_cndmask_b32_e64 v140, v140, 0, s[68:69]
	v_add_f32_e32 v141, v212, v140
	v_cvt_pk_bf16_f32 v140, v140, s0
	ds_write_b16 v209, v140 offset:2448
	v_sub_f32_e32 v140, v142, v183
	v_cmp_gt_f32_e32 vcc, s19, v140
	s_nop 1
	v_cndmask_b32_e32 v142, 0, v206, vcc
	v_add_f32_e32 v140, v140, v142
	v_exp_f32_e32 v140, v140
	v_cndmask_b32_e32 v142, 0, v207, vcc
	v_ldexp_f32 v140, v140, v142
	v_add_u32_e32 v142, 2, v144
	v_cmp_gt_u32_e32 vcc, s28, v142
	s_and_b64 s[68:69], s[10:11], vcc
	v_cndmask_b32_e64 v140, v140, 0, s[68:69]
	v_add_f32_e32 v142, v211, v140
	v_cvt_pk_bf16_f32 v140, v140, s0
	ds_write_b16 v209, v140 offset:2592
	v_sub_f32_e32 v140, v143, v183
	v_cmp_gt_f32_e32 vcc, s19, v140
	s_nop 1
	v_cndmask_b32_e32 v143, 0, v206, vcc
	v_add_f32_e32 v140, v140, v143
	v_exp_f32_e32 v140, v140
	v_cndmask_b32_e32 v143, 0, v207, vcc
	v_ldexp_f32 v140, v140, v143
	v_add_u32_e32 v143, 3, v144
	v_cmp_gt_u32_e32 vcc, s28, v143
	s_and_b64 s[68:69], s[10:11], vcc
	v_cmp_gt_f32_e32 vcc, s19, v136
	v_cndmask_b32_e64 v140, v140, 0, s[68:69]
	v_add_f32_e32 v143, v210, v140
	v_cndmask_b32_e32 v144, 0, v206, vcc
	v_add_f32_e32 v136, v136, v144
	v_exp_f32_e32 v136, v136
	v_cvt_pk_bf16_f32 v140, v140, s0
	ds_write_b16 v209, v140 offset:2736
	v_add_u32_e32 v140, s13, v171
	v_cndmask_b32_e32 v144, 0, v207, vcc
	v_cmp_gt_u32_e32 vcc, s28, v140
	v_ldexp_f32 v136, v136, v144
	s_and_b64 s[12:13], s[10:11], vcc
	v_cndmask_b32_e64 v136, v136, 0, s[12:13]
	v_add_f32_e32 v144, v145, v136
	v_cvt_pk_bf16_f32 v136, v136, s0
	ds_write_b16 v209, v136 offset:2336
	v_sub_f32_e32 v136, v137, v183
	v_cmp_gt_f32_e32 vcc, s19, v136
	s_nop 1
	v_cndmask_b32_e32 v137, 0, v206, vcc
	v_add_f32_e32 v136, v136, v137
	v_exp_f32_e32 v136, v136
	v_cndmask_b32_e32 v137, 0, v207, vcc
	v_ldexp_f32 v136, v136, v137
	v_add_u32_e32 v137, 1, v140
	v_cmp_gt_u32_e32 vcc, s28, v137
	s_and_b64 s[12:13], s[10:11], vcc
	v_cndmask_b32_e64 v136, v136, 0, s[12:13]
	v_add_f32_e32 v137, v141, v136
	v_cvt_pk_bf16_f32 v136, v136, s0
	ds_write_b16 v209, v136 offset:2480
	v_sub_f32_e32 v136, v138, v183
	v_cmp_gt_f32_e32 vcc, s19, v136
	v_add_u32_e32 v141, v187, v191
	s_nop 0
	v_cndmask_b32_e32 v138, 0, v206, vcc
	v_add_f32_e32 v136, v136, v138
	v_exp_f32_e32 v136, v136
	v_cndmask_b32_e32 v138, 0, v207, vcc
	v_ldexp_f32 v136, v136, v138
	v_add_u32_e32 v138, 2, v140
	v_cmp_gt_u32_e32 vcc, s28, v138
	s_and_b64 s[12:13], s[10:11], vcc
	v_cndmask_b32_e64 v136, v136, 0, s[12:13]
	v_add_f32_e32 v138, v142, v136
	v_cvt_pk_bf16_f32 v136, v136, s0
	ds_write_b16 v209, v136 offset:2624
	v_sub_f32_e32 v136, v139, v183
	v_cmp_gt_f32_e32 vcc, s19, v136
	s_nop 1
	v_cndmask_b32_e32 v139, 0, v206, vcc
	v_add_f32_e32 v136, v136, v139
	v_exp_f32_e32 v136, v136
	v_cndmask_b32_e32 v139, 0, v207, vcc
	v_ldexp_f32 v136, v136, v139
	v_add_u32_e32 v139, 3, v140
	v_cmp_gt_u32_e32 vcc, s28, v139
	s_and_b64 s[12:13], s[10:11], vcc
	v_cmp_gt_f32_e32 vcc, s19, v132
	v_cndmask_b32_e64 v136, v136, 0, s[12:13]
	v_add_f32_e32 v139, v143, v136
	v_cndmask_b32_e32 v140, 0, v206, vcc
	v_add_f32_e32 v132, v132, v140
	v_exp_f32_e32 v132, v132
	v_cvt_pk_bf16_f32 v136, v136, s0
	ds_write_b16 v209, v136 offset:2768
	v_add_u32_e32 v136, s30, v171
	v_cndmask_b32_e32 v140, 0, v207, vcc
	v_cmp_gt_u32_e32 vcc, s28, v136
	v_ldexp_f32 v132, v132, v140
	s_and_b64 s[12:13], s[10:11], vcc
	v_cndmask_b32_e64 v132, v132, 0, s[12:13]
	v_add_f32_e32 v140, v144, v132
	v_cvt_pk_bf16_f32 v132, v132, s0
	ds_write_b16 v209, v132 offset:2368
	v_sub_f32_e32 v132, v133, v183
	v_cmp_gt_f32_e32 vcc, s19, v132
	s_nop 1
	v_cndmask_b32_e32 v133, 0, v206, vcc
	v_add_f32_e32 v132, v132, v133
	v_exp_f32_e32 v132, v132
	v_cndmask_b32_e32 v133, 0, v207, vcc
	v_ldexp_f32 v132, v132, v133
	v_add_u32_e32 v133, 1, v136
	v_cmp_gt_u32_e32 vcc, s28, v133
	s_and_b64 s[12:13], s[10:11], vcc
	v_cndmask_b32_e64 v132, v132, 0, s[12:13]
	v_add_f32_e32 v133, v137, v132
	v_cvt_pk_bf16_f32 v132, v132, s0
	ds_write_b16 v209, v132 offset:2512
	v_sub_f32_e32 v132, v134, v183
	v_cmp_gt_f32_e32 vcc, s19, v132
	s_nop 1
	v_cndmask_b32_e32 v134, 0, v206, vcc
	v_add_f32_e32 v132, v132, v134
	v_exp_f32_e32 v132, v132
	v_cndmask_b32_e32 v134, 0, v207, vcc
	v_ldexp_f32 v132, v132, v134
	v_add_u32_e32 v134, 2, v136
	v_cmp_gt_u32_e32 vcc, s28, v134
	s_and_b64 s[12:13], s[10:11], vcc
	v_cndmask_b32_e64 v132, v132, 0, s[12:13]
	v_add_f32_e32 v134, v138, v132
	v_cvt_pk_bf16_f32 v132, v132, s0
	ds_write_b16 v209, v132 offset:2656
	v_sub_f32_e32 v132, v135, v183
	v_cmp_gt_f32_e32 vcc, s19, v132
	s_nop 1
	v_cndmask_b32_e32 v135, 0, v206, vcc
	v_add_f32_e32 v132, v132, v135
	v_exp_f32_e32 v132, v132
	v_cndmask_b32_e32 v135, 0, v207, vcc
	v_ldexp_f32 v132, v132, v135
	v_add_u32_e32 v135, 3, v136
	v_cmp_gt_u32_e32 vcc, s28, v135
	s_and_b64 s[12:13], s[10:11], vcc
	v_cmp_gt_f32_e32 vcc, s19, v128
	v_cndmask_b32_e64 v132, v132, 0, s[12:13]
	v_add_f32_e32 v135, v139, v132
; #define LAS __attribute__((address_space(3)))
; #define MFMA16(a, b, c) __builtin_amdgcn_mfma_f32_16x16x32_bf16((a), (b), (c), 0, 0, 0)
; #define ATT_STORE(bi, kr, vr) do { LAS unsigned char* _k = lds + (bi) * 17408; LAS unsigned char* _v = lds + 34816 + (bi) * 18432; \
;         *(LAS u32x4*)(_k + kkey0 * 272 + kseg * 16) = kr[0]; *(LAS u32x4*)(_k + (kkey0 + 32) * 272 + kseg * 16) = kr[1]; \
;         *(LAS u32x4*)(_v + vdim0 * 144 + vseg * 16) = vr[0]; *(LAS u32x4*)(_v + (vdim0 + 64) * 144 + vseg * 16) = vr[1]; } while (0)
; __device__ __forceinline__ void attn_item(const Params& P, int item, LAS unsigned char* lds, float mfix2) {
;     ...
;         asm volatile("s_waitcnt lgkmcnt(0)" ::: "memory");
; #pragma unroll
;         for (int ks = 0; ks < 2; ++ks) { bf16x8 pf[2];
; #pragma unroll
;             for (int rb = 0; rb < 2; ++rb) pf[rb] = *(const LAS bf16x8*)(Pw + (rb * 16 + r16) * 144 + ks * 64 + q4 * 16);
; #pragma unroll
;             for (int db = 0; db < 8; ++db) { const bf16x8 vf = *(const LAS bf16x8*)(vbuf + (db * 16 + r16) * 144 + ks * 64 + q4 * 16);
; #pragma unroll
;                 for (int rb = 0; rb < 2; ++rb) o[rb][db] = MFMA16(pf[rb], vf, o[rb][db]); } }
;         }
;         asm volatile("s_waitcnt lgkmcnt(0)" ::: "memory");
;           ATT_STORE(1, krA, vrA);
;           __syncthreads(); }
	v_cndmask_b32_e32 v136, 0, v206, vcc
	v_add_f32_e32 v128, v128, v136
	v_exp_f32_e32 v128, v128
	v_cvt_pk_bf16_f32 v132, v132, s0
	ds_write_b16 v209, v132 offset:2800
	v_add_u32_e32 v132, s21, v171
	v_cndmask_b32_e32 v136, 0, v207, vcc
	v_cmp_gt_u32_e32 vcc, s28, v132
	v_ldexp_f32 v128, v128, v136
	s_and_b64 s[12:13], s[10:11], vcc
	v_cndmask_b32_e64 v128, v128, 0, s[12:13]
	v_add_f32_e32 v213, v140, v128
	v_cvt_pk_bf16_f32 v128, v128, s0
	ds_write_b16 v209, v128 offset:2400
	v_sub_f32_e32 v128, v129, v183
	v_cmp_gt_f32_e32 vcc, s19, v128
	v_add_u32_e32 v140, v169, v191
	s_nop 0
	v_cndmask_b32_e32 v129, 0, v206, vcc
	v_add_f32_e32 v128, v128, v129
	v_exp_f32_e32 v128, v128
	v_cndmask_b32_e32 v129, 0, v207, vcc
	v_ldexp_f32 v128, v128, v129
	v_add_u32_e32 v129, 1, v132
	v_cmp_gt_u32_e32 vcc, s28, v129
	s_and_b64 s[12:13], s[10:11], vcc
	v_cndmask_b32_e64 v128, v128, 0, s[12:13]
	v_add_f32_e32 v212, v133, v128
	v_cvt_pk_bf16_f32 v128, v128, s0
	ds_write_b16 v209, v128 offset:2544
	v_sub_f32_e32 v128, v130, v183
	v_cmp_gt_f32_e32 vcc, s19, v128
	s_nop 1
	v_cndmask_b32_e32 v129, 0, v206, vcc
	v_add_f32_e32 v128, v128, v129
	v_exp_f32_e32 v128, v128
	v_cndmask_b32_e32 v129, 0, v207, vcc
	v_ldexp_f32 v128, v128, v129
	v_add_u32_e32 v129, 2, v132
	v_cmp_gt_u32_e32 vcc, s28, v129
	s_and_b64 s[12:13], s[10:11], vcc
	v_cndmask_b32_e64 v128, v128, 0, s[12:13]
	v_add_f32_e32 v211, v134, v128
	v_cvt_pk_bf16_f32 v128, v128, s0
	ds_write_b16 v209, v128 offset:2688
	v_sub_f32_e32 v128, v131, v183
	v_cmp_gt_f32_e32 vcc, s19, v128
	s_nop 1
	v_cndmask_b32_e32 v129, 0, v206, vcc
	v_add_f32_e32 v128, v128, v129
	v_exp_f32_e32 v128, v128
	v_cndmask_b32_e32 v129, 0, v207, vcc
	v_ldexp_f32 v128, v128, v129
	v_add_u32_e32 v129, 3, v132
	v_cmp_gt_u32_e32 vcc, s28, v129
	s_and_b64 s[10:11], s[10:11], vcc
	v_cndmask_b32_e64 v128, v128, 0, s[10:11]
	v_add_f32_e32 v210, v135, v128
	v_cvt_pk_bf16_f32 v128, v128, s0
	ds_write_b16 v209, v128 offset:2832
	s_waitcnt lgkmcnt(0)
	ds_read_b128 v[128:131], v140
	ds_read_b128 v[132:135], v140 offset:2304
	ds_read_b128 v[136:139], v141 offset:34816
	ds_read_b128 v[244:247], v141 offset:37120
	ds_read_b128 v[248:251], v141 offset:39424
	ds_read_b128 v[252:255], v141 offset:41728
	s_waitcnt lgkmcnt(3)
	v_mfma_f32_16x16x32_bf16 v[28:31], v[128:131], v[136:139], v[28:31]
	v_mfma_f32_16x16x32_bf16 v[0:3], v[132:135], v[136:139], v[0:3]
	ds_read_b128 v[136:139], v141 offset:44032
	s_waitcnt lgkmcnt(3)
	v_mfma_f32_16x16x32_bf16 v[32:35], v[128:131], v[244:247], v[32:35]
	v_mfma_f32_16x16x32_bf16 v[4:7], v[132:135], v[244:247], v[4:7]
	ds_read_b128 v[244:247], v141 offset:46336
	s_waitcnt lgkmcnt(3)
	v_mfma_f32_16x16x32_bf16 v[36:39], v[128:131], v[248:251], v[36:39]
	v_mfma_f32_16x16x32_bf16 v[8:11], v[132:135], v[248:251], v[8:11]
	ds_read_b128 v[248:251], v141 offset:48640
	s_waitcnt lgkmcnt(3)
	v_mfma_f32_16x16x32_bf16 v[68:71], v[128:131], v[252:255], v[68:71]
	v_mfma_f32_16x16x32_bf16 v[12:15], v[132:135], v[252:255], v[12:15]
	ds_read_b128 v[252:255], v141 offset:50944
	s_waitcnt lgkmcnt(3)
	v_mfma_f32_16x16x32_bf16 v[72:75], v[128:131], v[136:139], v[72:75]
	v_mfma_f32_16x16x32_bf16 v[16:19], v[132:135], v[136:139], v[16:19]
	ds_read_b128 v[136:139], v141 offset:34880
	s_waitcnt lgkmcnt(3)
	v_mfma_f32_16x16x32_bf16 v[80:83], v[128:131], v[244:247], v[80:83]
	v_mfma_f32_16x16x32_bf16 v[20:23], v[132:135], v[244:247], v[20:23]
	ds_read_b128 v[244:247], v141 offset:37184
	s_waitcnt lgkmcnt(3)
	v_mfma_f32_16x16x32_bf16 v[104:107], v[128:131], v[248:251], v[104:107]
	v_mfma_f32_16x16x32_bf16 v[24:27], v[132:135], v[248:251], v[24:27]
	ds_read_b128 v[248:251], v141 offset:39488
	s_waitcnt lgkmcnt(3)
	v_mfma_f32_16x16x32_bf16 v[124:127], v[128:131], v[252:255], v[124:127]
	v_mfma_f32_16x16x32_bf16 v[92:95], v[132:135], v[252:255], v[92:95]
	ds_read_b128 v[128:131], v140 offset:64
	ds_read_b128 v[132:135], v140 offset:2368
	ds_read_b128 v[252:255], v141 offset:41792
	s_waitcnt lgkmcnt(1)
	v_mfma_f32_16x16x32_bf16 v[28:31], v[128:131], v[136:139], v[28:31]
	v_mfma_f32_16x16x32_bf16 v[0:3], v[132:135], v[136:139], v[0:3]
	ds_read_b128 v[136:139], v141 offset:44096
	s_waitcnt lgkmcnt(2)
	v_mfma_f32_16x16x32_bf16 v[32:35], v[128:131], v[244:247], v[32:35]
	v_mfma_f32_16x16x32_bf16 v[4:7], v[132:135], v[244:247], v[4:7]
	ds_read_b128 v[244:247], v141 offset:46400
	s_waitcnt lgkmcnt(3)
	v_mfma_f32_16x16x32_bf16 v[36:39], v[128:131], v[248:251], v[36:39]
	v_mfma_f32_16x16x32_bf16 v[8:11], v[132:135], v[248:251], v[8:11]
	ds_read_b128 v[248:251], v141 offset:48704
	s_waitcnt lgkmcnt(3)
	v_mfma_f32_16x16x32_bf16 v[68:71], v[128:131], v[252:255], v[68:71]
	v_mfma_f32_16x16x32_bf16 v[12:15], v[132:135], v[252:255], v[12:15]
	ds_read_b128 v[252:255], v141 offset:51008
	s_waitcnt lgkmcnt(3)
	v_mfma_f32_16x16x32_bf16 v[72:75], v[128:131], v[136:139], v[72:75]
	v_mfma_f32_16x16x32_bf16 v[16:19], v[132:135], v[136:139], v[16:19]
	s_waitcnt lgkmcnt(2)
	v_mfma_f32_16x16x32_bf16 v[80:83], v[128:131], v[244:247], v[80:83]
	v_mfma_f32_16x16x32_bf16 v[20:23], v[132:135], v[244:247], v[20:23]
	s_waitcnt lgkmcnt(1)
	v_mfma_f32_16x16x32_bf16 v[104:107], v[128:131], v[248:251], v[104:107]
	v_mfma_f32_16x16x32_bf16 v[24:27], v[132:135], v[248:251], v[24:27]
	s_waitcnt lgkmcnt(0)
	v_mfma_f32_16x16x32_bf16 v[124:127], v[128:131], v[252:255], v[124:127]
	v_mfma_f32_16x16x32_bf16 v[92:95], v[132:135], v[252:255], v[92:95]
.LBB0_545:
	s_waitcnt lgkmcnt(0)
	s_cmp_gt_i32 s62, s57
	s_andn2_b64 vcc, exec, s[4:5]
	s_cbranch_vccnz .Latt_w0a
	s_waitcnt vmcnt(4)
	s_branch .Latt_wda

; #define ATT_LOAD(i, kr, vr) do { const int _p = ATT_POS0(i); \
;         kr[0] = *(const u32x4*)(Kb + (size_t)(_p + kkey0) * 128 + kseg * 8); kr[1] = *(const u32x4*)(Kb + (size_t)(_p + kkey0 + 32) * 128 + kseg * 8); \
;         vr[0] = *(const u32x4*)(Vtb + (size_t)vdim0 * KVLEN + _p + vseg * 8); vr[1] = *(const u32x4*)(Vtb + (size_t)(vdim0 + 64) * KVLEN + _p + vseg * 8); } while (0)
; #define ATT_STORE(bi, kr, vr) do { LAS unsigned char* _k = lds + (bi) * 17408; LAS unsigned char* _v = lds + 34816 + (bi) * 18432; \
;         *(LAS u32x4*)(_k + kkey0 * 272 + kseg * 16) = kr[0]; *(LAS u32x4*)(_k + (kkey0 + 32) * 272 + kseg * 16) = kr[1]; \
;         *(LAS u32x4*)(_v + vdim0 * 144 + vseg * 16) = vr[0]; *(LAS u32x4*)(_v + (vdim0 + 64) * 144 + vseg * 16) = vr[1]; } while (0)
; __device__ __forceinline__ void attn_item(const Params& P, int item, LAS unsigned char* lds, float mfix2) {
;     ...
;           ATT_STORE(1, krA, vrA);
;           __syncthreads(); }
;         { const int i = i0 + 1;
;           if (i + 2 < ntiles) ATT_LOAD(i + 2, krA, vrA);
.Latt_wda:
	ds_write_b128 v203, v[84:87] offset:17408
	ds_write_b128 v203, v[88:91] offset:26112
	ds_write_b128 v204, v[96:99] offset:53248
	ds_write_b128 v204, v[100:103] offset:62464
	s_waitcnt lgkmcnt(0)
	s_barrier
	s_cbranch_scc1 .LBB0_547
	s_cmp_lg_u32 s62, 3
	s_cselect_b32 s10, s61, 0xc0
	v_or_b32_e32 v84, s10, v185
	v_ashrrev_i32_e32 v85, 31, v84
	v_lshlrev_b64 v[84:85], 8, v[84:85]
	v_lshl_add_u64 v[84:85], v[176:177], 0, v[84:85]
	s_ashr_i32 s11, s10, 31
	v_add_co_u32_e32 v88, vcc, 0x2000, v84
	s_lshl_b64 s[10:11], s[10:11], 1
	s_nop 0
	v_addc_co_u32_e32 v89, vcc, 0, v85, vcc
	v_lshl_add_u64 v[96:97], v[172:173], 0, s[10:11]
	v_lshl_add_u64 v[100:101], v[174:175], 0, s[10:11]
	global_load_dwordx4 v[84:87], v[84:85], off
	s_nop 0
	global_load_dwordx4 v[88:91], v[88:89], off
	s_nop 0
	global_load_dwordx4 v[96:99], v[96:97], off
	s_nop 0
	global_load_dwordx4 v[100:103], v[100:101], off

; #define LAS __attribute__((address_space(3)))
; __device__ __forceinline__ bf16_t f2bf1(float x) { return (bf16_t)(cvt_pk_bf16(x, 0.f) & 0xffffu); }
; #define MFMA16(a, b, c) __builtin_amdgcn_mfma_f32_16x16x32_bf16((a), (b), (c), 0, 0, 0)
; __device__ __forceinline__ void attn_item(const Params& P, int item, LAS unsigned char* lds, float mfix2) {
;     ...
;         if (live) {
;         f32x4 s[2][4];
; #pragma unroll
;         for (int rb = 0; rb < 2; ++rb)
; #pragma unroll
;             for (int cb = 0; cb < 4; ++cb) s[rb][cb] = (f32x4){0.f, 0.f, 0.f, 0.f};
; #pragma unroll
;         for (int ks = 0; ks < 4; ++ks)
; #pragma unroll
;             for (int cb = 0; cb < 4; ++cb) { const bf16x8 kf = *(const LAS bf16x8*)(kbuf + (cb * 16 + r16) * 272 + ks * 64 + q4 * 16);
; #pragma unroll
;                 for (int rb = 0; rb < 2; ++rb) s[rb][cb] = MFMA16(qf[rb][ks], kf, s[rb][cb]); }
; #pragma unroll
;         for (int rb = 0; rb < 2; ++rb)
; #pragma unroll
;             for (int cb = 0; cb < 4; ++cb)
; #pragma unroll
;                 for (int j = 0; j < 4; ++j) {
;                     float p = exp2f(s[rb][cb][j] - mfix2);
;                     if (masked) { const int dq = (q0 + rw0 + rb * 16 + q4 * 4 + j) - (p0 - CTXL + cb * 16 + r16); if (dq > 128 || dq < -128) p = 0.f; }
;                     lsum[rb][j] += p;
;                     *(LAS bf16_t*)(Pw + (rb * 16 + q4 * 4 + j) * 144 + (cb * 16 + r16) * 2) = f2bf1(p);
;                 }
.LBB0_549:
	s_andn2_b64 vcc, exec, s[8:9]
	s_cbranch_vccnz .LBB0_551
	ds_read_b128 v[128:131], v205 offset:17408
	ds_read_b128 v[226:229], v205 offset:17472
	ds_read_b128 v[136:139], v205 offset:21760
	ds_read_b128 v[144:147], v205 offset:26112
	ds_read_b128 v[152:155], v205 offset:30464
	s_waitcnt lgkmcnt(4)
	v_mfma_f32_16x16x32_bf16 v[132:135], v[76:79], v[128:131], 0
	s_sub_i32 s8, 0x100, s10
	s_sub_i32 s9, 0xf0, s10
	s_sub_i32 s11, 0xe0, s10
	v_mfma_f32_16x16x32_bf16 v[128:131], v[52:55], v[128:131], 0
	s_sub_i32 s10, 0xd0, s10
	s_waitcnt lgkmcnt(3)
	v_mfma_f32_16x16x32_bf16 v[132:135], v[40:43], v[226:229], v[132:135]
	v_mfma_f32_16x16x32_bf16 v[128:131], v[56:59], v[226:229], v[128:131]
	ds_read_b128 v[226:229], v205 offset:21824
	s_waitcnt lgkmcnt(3)
	v_mfma_f32_16x16x32_bf16 v[140:143], v[76:79], v[136:139], 0
	v_mfma_f32_16x16x32_bf16 v[136:139], v[52:55], v[136:139], 0
	s_waitcnt lgkmcnt(0)
	v_mfma_f32_16x16x32_bf16 v[140:143], v[40:43], v[226:229], v[140:143]
	v_mfma_f32_16x16x32_bf16 v[136:139], v[56:59], v[226:229], v[136:139]
	ds_read_b128 v[226:229], v205 offset:26176
	v_mfma_f32_16x16x32_bf16 v[148:151], v[76:79], v[144:147], 0
	v_mfma_f32_16x16x32_bf16 v[144:147], v[52:55], v[144:147], 0
	s_waitcnt lgkmcnt(0)
	v_mfma_f32_16x16x32_bf16 v[148:151], v[40:43], v[226:229], v[148:151]
	v_mfma_f32_16x16x32_bf16 v[144:147], v[56:59], v[226:229], v[144:147]
	ds_read_b128 v[226:229], v205 offset:30528
	v_mfma_f32_16x16x32_bf16 v[218:221], v[76:79], v[152:155], 0
	v_mfma_f32_16x16x32_bf16 v[152:155], v[52:55], v[152:155], 0
	s_waitcnt lgkmcnt(0)
	v_mfma_f32_16x16x32_bf16 v[218:221], v[40:43], v[226:229], v[218:221]
	v_mfma_f32_16x16x32_bf16 v[152:155], v[56:59], v[226:229], v[152:155]
	ds_read_b128 v[226:229], v205 offset:17536
	s_waitcnt lgkmcnt(0)
	v_mfma_f32_16x16x32_bf16 v[132:135], v[44:47], v[226:229], v[132:135]
	v_mfma_f32_16x16x32_bf16 v[128:131], v[60:63], v[226:229], v[128:131]
	ds_read_b128 v[226:229], v205 offset:21888
	s_waitcnt lgkmcnt(0)
	v_mfma_f32_16x16x32_bf16 v[230:233], v[44:47], v[226:229], v[140:143]
	s_nop 2
	ds_read_b128 v[140:143], v205 offset:26240
	s_waitcnt lgkmcnt(0)
	v_mfma_f32_16x16x32_bf16 v[148:151], v[44:47], v[140:143], v[148:151]
	v_mfma_f32_16x16x32_bf16 v[144:147], v[60:63], v[140:143], v[144:147]
	ds_read_b128 v[140:143], v205 offset:30592
	v_mfma_f32_16x16x32_bf16 v[136:139], v[60:63], v[226:229], v[136:139]
	s_waitcnt lgkmcnt(0)
	v_mfma_f32_16x16x32_bf16 v[218:221], v[44:47], v[140:143], v[218:221]
	v_mfma_f32_16x16x32_bf16 v[226:229], v[60:63], v[140:143], v[152:155]
	ds_read_b128 v[140:143], v205 offset:17600
	s_waitcnt lgkmcnt(0)
	v_mfma_f32_16x16x32_bf16 v[234:237], v[48:51], v[140:143], v[132:135]
	v_mfma_f32_16x16x32_bf16 v[140:143], v[64:67], v[140:143], v[128:131]
	s_nop 2
	ds_read_b128 v[128:131], v205 offset:21952
	s_waitcnt lgkmcnt(0)
	v_mfma_f32_16x16x32_bf16 v[152:155], v[48:51], v[128:131], v[230:233]
	s_nop 1
	v_sub_f32_e32 v140, v140, v183
	s_nop 4
	v_sub_f32_e32 v152, v152, v183
	v_mfma_f32_16x16x32_bf16 v[136:139], v[64:67], v[128:131], v[136:139]
	ds_read_b128 v[128:131], v205 offset:26304
	s_waitcnt lgkmcnt(0)
	v_mfma_f32_16x16x32_bf16 v[148:151], v[48:51], v[128:131], v[148:151]
	s_nop 4
	v_sub_f32_e32 v136, v136, v183
	v_mfma_f32_16x16x32_bf16 v[132:135], v[64:67], v[128:131], v[144:147]
	ds_read_b128 v[128:131], v205 offset:30656
	v_sub_f32_e32 v148, v148, v183
	s_waitcnt lgkmcnt(0)
	v_mfma_f32_16x16x32_bf16 v[144:147], v[48:51], v[128:131], v[218:221]
	s_nop 2
	v_sub_f32_e32 v219, v234, v183
	v_cmp_gt_f32_e32 vcc, s19, v219
	v_add_u32_e32 v218, s8, v167
	s_nop 1
	v_sub_f32_e32 v144, v144, v183
	v_cndmask_b32_e32 v220, 0, v206, vcc
	v_add_f32_e32 v219, v219, v220
	v_exp_f32_e32 v219, v219
	v_cndmask_b32_e32 v220, 0, v207, vcc
	v_cmp_gt_u32_e32 vcc, s28, v218
	s_and_b64 s[12:13], s[6:7], vcc
	v_ldexp_f32 v219, v219, v220
	v_cndmask_b32_e64 v219, v219, 0, s[12:13]
	v_add_f32_e32 v217, v217, v219
	v_cvt_pk_bf16_f32 v219, v219, s0
	ds_write_b16 v209, v219
	v_sub_f32_e32 v219, v235, v183
	v_cmp_gt_f32_e32 vcc, s19, v219
	v_sub_f32_e32 v132, v132, v183
	v_mfma_f32_16x16x32_bf16 v[128:131], v[64:67], v[128:131], v[226:229]
	v_cndmask_b32_e32 v220, 0, v206, vcc
	v_add_f32_e32 v219, v219, v220
	v_exp_f32_e32 v219, v219
	v_cndmask_b32_e32 v220, 0, v207, vcc
	v_ldexp_f32 v219, v219, v220
	v_add_u32_e32 v220, 1, v218
	v_cmp_gt_u32_e32 vcc, s28, v220
	s_and_b64 s[12:13], s[6:7], vcc
	v_cndmask_b32_e64 v219, v219, 0, s[12:13]
	v_add_f32_e32 v216, v216, v219
	v_cvt_pk_bf16_f32 v219, v219, s0
	ds_write_b16 v209, v219 offset:144
	v_sub_f32_e32 v219, v236, v183
	v_cmp_gt_f32_e32 vcc, s19, v219
	v_sub_f32_e32 v128, v128, v183
	s_nop 0
	v_cndmask_b32_e32 v220, 0, v206, vcc
	v_add_f32_e32 v219, v219, v220
	v_exp_f32_e32 v219, v219
	v_cndmask_b32_e32 v220, 0, v207, vcc
	v_ldexp_f32 v219, v219, v220
	v_add_u32_e32 v220, 2, v218
	v_cmp_gt_u32_e32 vcc, s28, v220
	s_and_b64 s[12:13], s[6:7], vcc
	v_cndmask_b32_e64 v219, v219, 0, s[12:13]
	v_add_f32_e32 v215, v215, v219
	v_cvt_pk_bf16_f32 v219, v219, s0
	ds_write_b16 v209, v219 offset:288
	v_sub_f32_e32 v219, v237, v183
	v_cmp_gt_f32_e32 vcc, s19, v219
	v_add_u32_e32 v218, 3, v218
	s_nop 0
	v_cndmask_b32_e32 v220, 0, v206, vcc
	v_add_f32_e32 v219, v219, v220
	v_exp_f32_e32 v219, v219
	v_cndmask_b32_e32 v220, 0, v207, vcc
	v_cmp_gt_u32_e32 vcc, s28, v218
	s_and_b64 s[12:13], s[6:7], vcc
	v_ldexp_f32 v219, v219, v220
	v_cmp_gt_f32_e32 vcc, s19, v152
	v_cndmask_b32_e64 v218, v219, 0, s[12:13]
	v_add_f32_e32 v214, v214, v218
	v_cndmask_b32_e32 v219, 0, v206, vcc
	v_add_f32_e32 v152, v152, v219
	v_exp_f32_e32 v152, v152
	v_cvt_pk_bf16_f32 v218, v218, s0
; #define LAS __attribute__((address_space(3)))
; __device__ __forceinline__ bf16_t f2bf1(float x) { return (bf16_t)(cvt_pk_bf16(x, 0.f) & 0xffffu); }
; __device__ __forceinline__ void attn_item(const Params& P, int item, LAS unsigned char* lds, float mfix2) {
;     ...
;         for (int rb = 0; rb < 2; ++rb)
; #pragma unroll
;             for (int cb = 0; cb < 4; ++cb)
; #pragma unroll
;                 for (int j = 0; j < 4; ++j) {
;                     float p = exp2f(s[rb][cb][j] - mfix2);
;                     if (masked) { const int dq = (q0 + rw0 + rb * 16 + q4 * 4 + j) - (p0 - CTXL + cb * 16 + r16); if (dq > 128 || dq < -128) p = 0.f; }
;                     lsum[rb][j] += p;
;                     *(LAS bf16_t*)(Pw + (rb * 16 + q4 * 4 + j) * 144 + (cb * 16 + r16) * 2) = f2bf1(p);
;                 }
	ds_write_b16 v209, v218 offset:432
	v_add_u32_e32 v218, s9, v167
	v_cndmask_b32_e32 v219, 0, v207, vcc
	v_cmp_gt_u32_e32 vcc, s28, v218
	v_ldexp_f32 v152, v152, v219
	s_and_b64 s[12:13], s[6:7], vcc
	v_cndmask_b32_e64 v152, v152, 0, s[12:13]
	v_add_f32_e32 v217, v217, v152
	v_cvt_pk_bf16_f32 v152, v152, s0
	ds_write_b16 v209, v152 offset:32
	v_sub_f32_e32 v152, v153, v183
	v_cmp_gt_f32_e32 vcc, s19, v152
	s_nop 1
	v_cndmask_b32_e32 v153, 0, v206, vcc
	v_add_f32_e32 v152, v152, v153
	v_exp_f32_e32 v152, v152
	v_cndmask_b32_e32 v153, 0, v207, vcc
	v_ldexp_f32 v152, v152, v153
	v_add_u32_e32 v153, 1, v218
	v_cmp_gt_u32_e32 vcc, s28, v153
	s_and_b64 s[12:13], s[6:7], vcc
	v_cndmask_b32_e64 v152, v152, 0, s[12:13]
	v_add_f32_e32 v153, v216, v152
	v_cvt_pk_bf16_f32 v152, v152, s0
	ds_write_b16 v209, v152 offset:176
	v_sub_f32_e32 v152, v154, v183
	v_cmp_gt_f32_e32 vcc, s19, v152
	s_nop 1
	v_cndmask_b32_e32 v154, 0, v206, vcc
	v_add_f32_e32 v152, v152, v154
	v_exp_f32_e32 v152, v152
	v_cndmask_b32_e32 v154, 0, v207, vcc
	v_ldexp_f32 v152, v152, v154
	v_add_u32_e32 v154, 2, v218
	v_cmp_gt_u32_e32 vcc, s28, v154
	s_and_b64 s[12:13], s[6:7], vcc
	v_cndmask_b32_e64 v152, v152, 0, s[12:13]
	v_add_f32_e32 v154, v215, v152
	v_cvt_pk_bf16_f32 v152, v152, s0
	ds_write_b16 v209, v152 offset:320
	v_sub_f32_e32 v152, v155, v183
	v_cmp_gt_f32_e32 vcc, s19, v152
	s_nop 1
	v_cndmask_b32_e32 v155, 0, v206, vcc
	v_add_f32_e32 v152, v152, v155
	v_exp_f32_e32 v152, v152
	v_cndmask_b32_e32 v155, 0, v207, vcc
	v_ldexp_f32 v152, v152, v155
	v_add_u32_e32 v155, 3, v218
	v_cmp_gt_u32_e32 vcc, s28, v155
	s_and_b64 s[12:13], s[6:7], vcc
	v_cndmask_b32_e64 v152, v152, 0, s[12:13]
	v_cmp_gt_f32_e32 vcc, s19, v148
	v_add_f32_e32 v155, v214, v152
	v_cvt_pk_bf16_f32 v152, v152, s0
	v_cndmask_b32_e32 v214, 0, v206, vcc
	v_add_f32_e32 v148, v148, v214
	v_exp_f32_e32 v148, v148
	ds_write_b16 v209, v152 offset:464
	v_add_u32_e32 v152, s11, v167
	v_cndmask_b32_e32 v214, 0, v207, vcc
	v_cmp_gt_u32_e32 vcc, s28, v152
	v_ldexp_f32 v148, v148, v214
	s_and_b64 s[12:13], s[6:7], vcc
	v_cndmask_b32_e64 v148, v148, 0, s[12:13]
	v_add_f32_e32 v214, v217, v148
	v_cvt_pk_bf16_f32 v148, v148, s0
	ds_write_b16 v209, v148 offset:64
	v_sub_f32_e32 v148, v149, v183
	v_cmp_gt_f32_e32 vcc, s19, v148
	s_nop 1
	v_cndmask_b32_e32 v149, 0, v206, vcc
	v_add_f32_e32 v148, v148, v149
	v_exp_f32_e32 v148, v148
	v_cndmask_b32_e32 v149, 0, v207, vcc
	v_ldexp_f32 v148, v148, v149
	v_add_u32_e32 v149, 1, v152
	v_cmp_gt_u32_e32 vcc, s28, v149
	s_and_b64 s[12:13], s[6:7], vcc
	v_cndmask_b32_e64 v148, v148, 0, s[12:13]
	v_add_f32_e32 v149, v153, v148
	v_cvt_pk_bf16_f32 v148, v148, s0
	ds_write_b16 v209, v148 offset:208
	v_sub_f32_e32 v148, v150, v183
	v_cmp_gt_f32_e32 vcc, s19, v148
	s_nop 1
	v_cndmask_b32_e32 v150, 0, v206, vcc
	v_add_f32_e32 v148, v148, v150
	v_exp_f32_e32 v148, v148
	v_cndmask_b32_e32 v150, 0, v207, vcc
	v_ldexp_f32 v148, v148, v150
	v_add_u32_e32 v150, 2, v152
	v_cmp_gt_u32_e32 vcc, s28, v150
	s_and_b64 s[12:13], s[6:7], vcc
	v_cndmask_b32_e64 v148, v148, 0, s[12:13]
	v_add_f32_e32 v150, v154, v148
	v_cvt_pk_bf16_f32 v148, v148, s0
	ds_write_b16 v209, v148 offset:352
	v_sub_f32_e32 v148, v151, v183
	v_cmp_gt_f32_e32 vcc, s19, v148
	s_nop 1
	v_cndmask_b32_e32 v151, 0, v206, vcc
	v_add_f32_e32 v148, v148, v151
	v_exp_f32_e32 v148, v148
	v_cndmask_b32_e32 v151, 0, v207, vcc
	v_ldexp_f32 v148, v148, v151
	v_add_u32_e32 v151, 3, v152
	v_cmp_gt_u32_e32 vcc, s28, v151
	s_and_b64 s[12:13], s[6:7], vcc
	v_cmp_gt_f32_e32 vcc, s19, v144
	v_cndmask_b32_e64 v148, v148, 0, s[12:13]
	v_add_f32_e32 v151, v155, v148
	v_cndmask_b32_e32 v152, 0, v206, vcc
	v_add_f32_e32 v144, v144, v152
	v_exp_f32_e32 v144, v144
	v_cvt_pk_bf16_f32 v148, v148, s0
	ds_write_b16 v209, v148 offset:496
	v_add_u32_e32 v148, s10, v167
	v_cndmask_b32_e32 v152, 0, v207, vcc
	v_cmp_gt_u32_e32 vcc, s28, v148
	v_ldexp_f32 v144, v144, v152
	s_and_b64 s[12:13], s[6:7], vcc
	v_cndmask_b32_e64 v144, v144, 0, s[12:13]
	v_add_f32_e32 v217, v214, v144
	v_cvt_pk_bf16_f32 v144, v144, s0
	ds_write_b16 v209, v144 offset:96
	v_sub_f32_e32 v144, v145, v183
	v_cmp_gt_f32_e32 vcc, s19, v144
	s_nop 1
	v_cndmask_b32_e32 v145, 0, v206, vcc
	v_add_f32_e32 v144, v144, v145
	v_exp_f32_e32 v144, v144
	v_cndmask_b32_e32 v145, 0, v207, vcc
	v_ldexp_f32 v144, v144, v145
	v_add_u32_e32 v145, 1, v148
	v_cmp_gt_u32_e32 vcc, s28, v145
	s_and_b64 s[12:13], s[6:7], vcc
	v_cndmask_b32_e64 v144, v144, 0, s[12:13]
	v_add_f32_e32 v216, v149, v144
	v_cvt_pk_bf16_f32 v144, v144, s0
	ds_write_b16 v209, v144 offset:240
	v_sub_f32_e32 v144, v146, v183
	v_cmp_gt_f32_e32 vcc, s19, v144
	s_nop 1
	v_cndmask_b32_e32 v145, 0, v206, vcc
	v_add_f32_e32 v144, v144, v145
	v_exp_f32_e32 v144, v144
	v_cndmask_b32_e32 v145, 0, v207, vcc
	v_ldexp_f32 v144, v144, v145
	v_add_u32_e32 v145, 2, v148
	v_cmp_gt_u32_e32 vcc, s28, v145
	s_and_b64 s[12:13], s[6:7], vcc
	v_cndmask_b32_e64 v144, v144, 0, s[12:13]
	v_add_f32_e32 v215, v150, v144
	v_cvt_pk_bf16_f32 v144, v144, s0
	ds_write_b16 v209, v144 offset:384
	v_sub_f32_e32 v144, v147, v183
	v_cmp_gt_f32_e32 vcc, s19, v144
	s_nop 1
	v_cndmask_b32_e32 v145, 0, v206, vcc
	v_add_f32_e32 v144, v144, v145
	v_exp_f32_e32 v144, v144
	v_cndmask_b32_e32 v145, 0, v207, vcc
	v_ldexp_f32 v144, v144, v145
	v_add_u32_e32 v145, 3, v148
	v_cmp_gt_u32_e32 vcc, s28, v145
	s_and_b64 s[12:13], s[6:7], vcc
	v_cmp_gt_f32_e32 vcc, s19, v140
	v_cndmask_b32_e64 v144, v144, 0, s[12:13]
	v_add_f32_e32 v214, v151, v144
	v_cndmask_b32_e32 v145, 0, v206, vcc
	v_add_f32_e32 v140, v140, v145
	v_exp_f32_e32 v140, v140
	v_cvt_pk_bf16_f32 v144, v144, s0
	ds_write_b16 v209, v144 offset:528
; #define LAS __attribute__((address_space(3)))
; __device__ __forceinline__ bf16_t f2bf1(float x) { return (bf16_t)(cvt_pk_bf16(x, 0.f) & 0xffffu); }
; __device__ __forceinline__ void attn_item(const Params& P, int item, LAS unsigned char* lds, float mfix2) {
;     ...
;         for (int rb = 0; rb < 2; ++rb)
; #pragma unroll
;             for (int cb = 0; cb < 4; ++cb)
; #pragma unroll
;                 for (int j = 0; j < 4; ++j) {
;                     float p = exp2f(s[rb][cb][j] - mfix2);
;                     if (masked) { const int dq = (q0 + rw0 + rb * 16 + q4 * 4 + j) - (p0 - CTXL + cb * 16 + r16); if (dq > 128 || dq < -128) p = 0.f; }
;                     lsum[rb][j] += p;
;                     *(LAS bf16_t*)(Pw + (rb * 16 + q4 * 4 + j) * 144 + (cb * 16 + r16) * 2) = f2bf1(p);
;                 }
	v_add_u32_e32 v144, s8, v171
	v_cndmask_b32_e32 v145, 0, v207, vcc
	v_cmp_gt_u32_e32 vcc, s28, v144
	v_ldexp_f32 v140, v140, v145
	s_and_b64 s[12:13], s[6:7], vcc
	v_cndmask_b32_e64 v140, v140, 0, s[12:13]
	v_add_f32_e32 v145, v213, v140
	v_cvt_pk_bf16_f32 v140, v140, s0
	ds_write_b16 v209, v140 offset:2304
	v_sub_f32_e32 v140, v141, v183
	v_cmp_gt_f32_e32 vcc, s19, v140
	s_nop 1
	v_cndmask_b32_e32 v141, 0, v206, vcc
	v_add_f32_e32 v140, v140, v141
	v_exp_f32_e32 v140, v140
	v_cndmask_b32_e32 v141, 0, v207, vcc
	v_ldexp_f32 v140, v140, v141
	v_add_u32_e32 v141, 1, v144
	v_cmp_gt_u32_e32 vcc, s28, v141
	s_and_b64 s[12:13], s[6:7], vcc
	v_cndmask_b32_e64 v140, v140, 0, s[12:13]
	v_add_f32_e32 v141, v212, v140
	v_cvt_pk_bf16_f32 v140, v140, s0
	ds_write_b16 v209, v140 offset:2448
	v_sub_f32_e32 v140, v142, v183
	v_cmp_gt_f32_e32 vcc, s19, v140
	s_nop 1
	v_cndmask_b32_e32 v142, 0, v206, vcc
	v_add_f32_e32 v140, v140, v142
	v_exp_f32_e32 v140, v140
	v_cndmask_b32_e32 v142, 0, v207, vcc
	v_ldexp_f32 v140, v140, v142
	v_add_u32_e32 v142, 2, v144
	v_cmp_gt_u32_e32 vcc, s28, v142
	s_and_b64 s[12:13], s[6:7], vcc
	v_cndmask_b32_e64 v140, v140, 0, s[12:13]
	v_add_f32_e32 v142, v211, v140
	v_cvt_pk_bf16_f32 v140, v140, s0
	ds_write_b16 v209, v140 offset:2592
	v_sub_f32_e32 v140, v143, v183
	v_cmp_gt_f32_e32 vcc, s19, v140
	s_nop 1
	v_cndmask_b32_e32 v143, 0, v206, vcc
	v_add_f32_e32 v140, v140, v143
	v_exp_f32_e32 v140, v140
	v_cndmask_b32_e32 v143, 0, v207, vcc
	v_ldexp_f32 v140, v140, v143
	v_add_u32_e32 v143, 3, v144
	v_cmp_gt_u32_e32 vcc, s28, v143
	s_and_b64 s[12:13], s[6:7], vcc
	v_cmp_gt_f32_e32 vcc, s19, v136
	v_cndmask_b32_e64 v140, v140, 0, s[12:13]
	v_add_f32_e32 v143, v210, v140
	v_cndmask_b32_e32 v144, 0, v206, vcc
	v_add_f32_e32 v136, v136, v144
	v_exp_f32_e32 v136, v136
	v_cvt_pk_bf16_f32 v140, v140, s0
	ds_write_b16 v209, v140 offset:2736
	v_add_u32_e32 v140, s9, v171
	v_cndmask_b32_e32 v144, 0, v207, vcc
	v_cmp_gt_u32_e32 vcc, s28, v140
	v_ldexp_f32 v136, v136, v144
	s_and_b64 s[8:9], s[6:7], vcc
	v_cndmask_b32_e64 v136, v136, 0, s[8:9]
	v_add_f32_e32 v144, v145, v136
	v_cvt_pk_bf16_f32 v136, v136, s0
	ds_write_b16 v209, v136 offset:2336
	v_sub_f32_e32 v136, v137, v183
	v_cmp_gt_f32_e32 vcc, s19, v136
	s_nop 1
	v_cndmask_b32_e32 v137, 0, v206, vcc
	v_add_f32_e32 v136, v136, v137
	v_exp_f32_e32 v136, v136
	v_cndmask_b32_e32 v137, 0, v207, vcc
	v_ldexp_f32 v136, v136, v137
	v_add_u32_e32 v137, 1, v140
	v_cmp_gt_u32_e32 vcc, s28, v137
	s_and_b64 s[8:9], s[6:7], vcc
	v_cndmask_b32_e64 v136, v136, 0, s[8:9]
	v_add_f32_e32 v137, v141, v136
	v_cvt_pk_bf16_f32 v136, v136, s0
	ds_write_b16 v209, v136 offset:2480
	v_sub_f32_e32 v136, v138, v183
	v_cmp_gt_f32_e32 vcc, s19, v136
	v_add_u32_e32 v141, v187, v191
	s_nop 0
	v_cndmask_b32_e32 v138, 0, v206, vcc
	v_add_f32_e32 v136, v136, v138
	v_exp_f32_e32 v136, v136
	v_cndmask_b32_e32 v138, 0, v207, vcc
	v_ldexp_f32 v136, v136, v138
	v_add_u32_e32 v138, 2, v140
	v_cmp_gt_u32_e32 vcc, s28, v138
	s_and_b64 s[8:9], s[6:7], vcc
	v_cndmask_b32_e64 v136, v136, 0, s[8:9]
	v_add_f32_e32 v138, v142, v136
	v_cvt_pk_bf16_f32 v136, v136, s0
	ds_write_b16 v209, v136 offset:2624
	v_sub_f32_e32 v136, v139, v183
	v_cmp_gt_f32_e32 vcc, s19, v136
	s_nop 1
	v_cndmask_b32_e32 v139, 0, v206, vcc
	v_add_f32_e32 v136, v136, v139
	v_exp_f32_e32 v136, v136
	v_cndmask_b32_e32 v139, 0, v207, vcc
	v_ldexp_f32 v136, v136, v139
	v_add_u32_e32 v139, 3, v140
	v_cmp_gt_u32_e32 vcc, s28, v139
	s_and_b64 s[8:9], s[6:7], vcc
	v_cmp_gt_f32_e32 vcc, s19, v132
	v_cndmask_b32_e64 v136, v136, 0, s[8:9]
	v_add_f32_e32 v139, v143, v136
	v_cndmask_b32_e32 v140, 0, v206, vcc
	v_add_f32_e32 v132, v132, v140
	v_exp_f32_e32 v132, v132
	v_cvt_pk_bf16_f32 v136, v136, s0
	ds_write_b16 v209, v136 offset:2768
	v_add_u32_e32 v136, s11, v171
	v_cndmask_b32_e32 v140, 0, v207, vcc
	v_cmp_gt_u32_e32 vcc, s28, v136
	v_ldexp_f32 v132, v132, v140
	s_and_b64 s[8:9], s[6:7], vcc
	v_cndmask_b32_e64 v132, v132, 0, s[8:9]
	v_add_f32_e32 v140, v144, v132
	v_cvt_pk_bf16_f32 v132, v132, s0
	ds_write_b16 v209, v132 offset:2368
	v_sub_f32_e32 v132, v133, v183
	v_cmp_gt_f32_e32 vcc, s19, v132
	s_nop 1
	v_cndmask_b32_e32 v133, 0, v206, vcc
	v_add_f32_e32 v132, v132, v133
	v_exp_f32_e32 v132, v132
	v_cndmask_b32_e32 v133, 0, v207, vcc
	v_ldexp_f32 v132, v132, v133
	v_add_u32_e32 v133, 1, v136
	v_cmp_gt_u32_e32 vcc, s28, v133
	s_and_b64 s[8:9], s[6:7], vcc
	v_cndmask_b32_e64 v132, v132, 0, s[8:9]
	v_add_f32_e32 v133, v137, v132
	v_cvt_pk_bf16_f32 v132, v132, s0
	ds_write_b16 v209, v132 offset:2512
	v_sub_f32_e32 v132, v134, v183
	v_cmp_gt_f32_e32 vcc, s19, v132
	s_nop 1
	v_cndmask_b32_e32 v134, 0, v206, vcc
	v_add_f32_e32 v132, v132, v134
	v_exp_f32_e32 v132, v132
	v_cndmask_b32_e32 v134, 0, v207, vcc
	v_ldexp_f32 v132, v132, v134
	v_add_u32_e32 v134, 2, v136
	v_cmp_gt_u32_e32 vcc, s28, v134
	s_and_b64 s[8:9], s[6:7], vcc
	v_cndmask_b32_e64 v132, v132, 0, s[8:9]
	v_add_f32_e32 v134, v138, v132
	v_cvt_pk_bf16_f32 v132, v132, s0
	ds_write_b16 v209, v132 offset:2656
	v_sub_f32_e32 v132, v135, v183
	v_cmp_gt_f32_e32 vcc, s19, v132
	s_nop 1
	v_cndmask_b32_e32 v135, 0, v206, vcc
	v_add_f32_e32 v132, v132, v135
	v_exp_f32_e32 v132, v132
	v_cndmask_b32_e32 v135, 0, v207, vcc
	v_ldexp_f32 v132, v132, v135
	v_add_u32_e32 v135, 3, v136
	v_cmp_gt_u32_e32 vcc, s28, v135
	s_and_b64 s[8:9], s[6:7], vcc
	v_cmp_gt_f32_e32 vcc, s19, v128
	v_cndmask_b32_e64 v132, v132, 0, s[8:9]
	v_add_f32_e32 v135, v139, v132
	v_cndmask_b32_e32 v136, 0, v206, vcc
; #define LAS __attribute__((address_space(3)))
; #define MFMA16(a, b, c) __builtin_amdgcn_mfma_f32_16x16x32_bf16((a), (b), (c), 0, 0, 0)
; #define ATT_STORE(bi, kr, vr) do { LAS unsigned char* _k = lds + (bi) * 17408; LAS unsigned char* _v = lds + 34816 + (bi) * 18432; \
;         *(LAS u32x4*)(_k + kkey0 * 272 + kseg * 16) = kr[0]; *(LAS u32x4*)(_k + (kkey0 + 32) * 272 + kseg * 16) = kr[1]; \
;         *(LAS u32x4*)(_v + vdim0 * 144 + vseg * 16) = vr[0]; *(LAS u32x4*)(_v + (vdim0 + 64) * 144 + vseg * 16) = vr[1]; } while (0)
; __device__ __forceinline__ void attn_item(const Params& P, int item, LAS unsigned char* lds, float mfix2) {
;     ...
;         asm volatile("s_waitcnt lgkmcnt(0)" ::: "memory");
; #pragma unroll
;         for (int ks = 0; ks < 2; ++ks) { bf16x8 pf[2];
; #pragma unroll
;             for (int rb = 0; rb < 2; ++rb) pf[rb] = *(const LAS bf16x8*)(Pw + (rb * 16 + r16) * 144 + ks * 64 + q4 * 16);
; #pragma unroll
;             for (int db = 0; db < 8; ++db) { const bf16x8 vf = *(const LAS bf16x8*)(vbuf + (db * 16 + r16) * 144 + ks * 64 + q4 * 16);
; #pragma unroll
;                 for (int rb = 0; rb < 2; ++rb) o[rb][db] = MFMA16(pf[rb], vf, o[rb][db]); } }
;         }
;         asm volatile("s_waitcnt lgkmcnt(0)" ::: "memory");
;           if (i + 1 < ntiles) ATT_STORE(0, krB, vrB);
;           __syncthreads(); }
	v_add_f32_e32 v128, v128, v136
	v_exp_f32_e32 v128, v128
	v_cvt_pk_bf16_f32 v132, v132, s0
	ds_write_b16 v209, v132 offset:2800
	v_add_u32_e32 v132, s10, v171
	v_cndmask_b32_e32 v136, 0, v207, vcc
	v_cmp_gt_u32_e32 vcc, s28, v132
	v_ldexp_f32 v128, v128, v136
	s_and_b64 s[8:9], s[6:7], vcc
	v_cndmask_b32_e64 v128, v128, 0, s[8:9]
	v_add_f32_e32 v213, v140, v128
	v_cvt_pk_bf16_f32 v128, v128, s0
	ds_write_b16 v209, v128 offset:2400
	v_sub_f32_e32 v128, v129, v183
	v_cmp_gt_f32_e32 vcc, s19, v128
	v_add_u32_e32 v140, v169, v191
	s_nop 0
	v_cndmask_b32_e32 v129, 0, v206, vcc
	v_add_f32_e32 v128, v128, v129
	v_exp_f32_e32 v128, v128
	v_cndmask_b32_e32 v129, 0, v207, vcc
	v_ldexp_f32 v128, v128, v129
	v_add_u32_e32 v129, 1, v132
	v_cmp_gt_u32_e32 vcc, s28, v129
	s_and_b64 s[8:9], s[6:7], vcc
	v_cndmask_b32_e64 v128, v128, 0, s[8:9]
	v_add_f32_e32 v212, v133, v128
	v_cvt_pk_bf16_f32 v128, v128, s0
	ds_write_b16 v209, v128 offset:2544
	v_sub_f32_e32 v128, v130, v183
	v_cmp_gt_f32_e32 vcc, s19, v128
	s_nop 1
	v_cndmask_b32_e32 v129, 0, v206, vcc
	v_add_f32_e32 v128, v128, v129
	v_exp_f32_e32 v128, v128
	v_cndmask_b32_e32 v129, 0, v207, vcc
	v_ldexp_f32 v128, v128, v129
	v_add_u32_e32 v129, 2, v132
	v_cmp_gt_u32_e32 vcc, s28, v129
	s_and_b64 s[8:9], s[6:7], vcc
	v_cndmask_b32_e64 v128, v128, 0, s[8:9]
	v_add_f32_e32 v211, v134, v128
	v_cvt_pk_bf16_f32 v128, v128, s0
	ds_write_b16 v209, v128 offset:2688
	v_sub_f32_e32 v128, v131, v183
	v_cmp_gt_f32_e32 vcc, s19, v128
	s_nop 1
	v_cndmask_b32_e32 v129, 0, v206, vcc
	v_add_f32_e32 v128, v128, v129
	v_exp_f32_e32 v128, v128
	v_cndmask_b32_e32 v129, 0, v207, vcc
	v_ldexp_f32 v128, v128, v129
	v_add_u32_e32 v129, 3, v132
	v_cmp_gt_u32_e32 vcc, s28, v129
	s_and_b64 s[6:7], s[6:7], vcc
	v_cndmask_b32_e64 v128, v128, 0, s[6:7]
	v_add_f32_e32 v210, v135, v128
	v_cvt_pk_bf16_f32 v128, v128, s0
	ds_write_b16 v209, v128 offset:2832
	s_waitcnt lgkmcnt(0)
	ds_read_b128 v[128:131], v140
	ds_read_b128 v[132:135], v140 offset:2304
	ds_read_b128 v[136:139], v141 offset:53248
	ds_read_b128 v[244:247], v141 offset:55552
	ds_read_b128 v[248:251], v141 offset:57856
	ds_read_b128 v[252:255], v141 offset:60160
	s_waitcnt lgkmcnt(3)
	v_mfma_f32_16x16x32_bf16 v[28:31], v[128:131], v[136:139], v[28:31]
	v_mfma_f32_16x16x32_bf16 v[0:3], v[132:135], v[136:139], v[0:3]
	ds_read_b128 v[136:139], v141 offset:62464
	s_waitcnt lgkmcnt(3)
	v_mfma_f32_16x16x32_bf16 v[32:35], v[128:131], v[244:247], v[32:35]
	v_mfma_f32_16x16x32_bf16 v[4:7], v[132:135], v[244:247], v[4:7]
	ds_read_b128 v[244:247], v141 offset:64768
	s_waitcnt lgkmcnt(3)
	v_mfma_f32_16x16x32_bf16 v[36:39], v[128:131], v[248:251], v[36:39]
	v_mfma_f32_16x16x32_bf16 v[8:11], v[132:135], v[248:251], v[8:11]
	ds_read_b128 v[248:251], v200 offset:53248
	s_waitcnt lgkmcnt(3)
	v_mfma_f32_16x16x32_bf16 v[68:71], v[128:131], v[252:255], v[68:71]
	v_mfma_f32_16x16x32_bf16 v[12:15], v[132:135], v[252:255], v[12:15]
	ds_read_b128 v[252:255], v201 offset:53248
	s_waitcnt lgkmcnt(3)
	v_mfma_f32_16x16x32_bf16 v[72:75], v[128:131], v[136:139], v[72:75]
	v_mfma_f32_16x16x32_bf16 v[16:19], v[132:135], v[136:139], v[16:19]
	ds_read_b128 v[136:139], v141 offset:53312
	s_waitcnt lgkmcnt(3)
	v_mfma_f32_16x16x32_bf16 v[80:83], v[128:131], v[244:247], v[80:83]
	v_mfma_f32_16x16x32_bf16 v[20:23], v[132:135], v[244:247], v[20:23]
	ds_read_b128 v[244:247], v141 offset:55616
	s_waitcnt lgkmcnt(3)
	v_mfma_f32_16x16x32_bf16 v[104:107], v[128:131], v[248:251], v[104:107]
	v_mfma_f32_16x16x32_bf16 v[24:27], v[132:135], v[248:251], v[24:27]
	ds_read_b128 v[248:251], v141 offset:57920
	s_waitcnt lgkmcnt(3)
	v_mfma_f32_16x16x32_bf16 v[124:127], v[128:131], v[252:255], v[124:127]
	v_mfma_f32_16x16x32_bf16 v[92:95], v[132:135], v[252:255], v[92:95]
	ds_read_b128 v[128:131], v140 offset:64
	ds_read_b128 v[132:135], v140 offset:2368
	ds_read_b128 v[252:255], v141 offset:60224
	s_waitcnt lgkmcnt(1)
	v_mfma_f32_16x16x32_bf16 v[28:31], v[128:131], v[136:139], v[28:31]
	v_mfma_f32_16x16x32_bf16 v[0:3], v[132:135], v[136:139], v[0:3]
	ds_read_b128 v[136:139], v141 offset:62528
	s_waitcnt lgkmcnt(2)
	v_mfma_f32_16x16x32_bf16 v[32:35], v[128:131], v[244:247], v[32:35]
	v_mfma_f32_16x16x32_bf16 v[4:7], v[132:135], v[244:247], v[4:7]
	ds_read_b128 v[244:247], v141 offset:64832
	s_waitcnt lgkmcnt(3)
	v_mfma_f32_16x16x32_bf16 v[36:39], v[128:131], v[248:251], v[36:39]
	v_mfma_f32_16x16x32_bf16 v[8:11], v[132:135], v[248:251], v[8:11]
	ds_read_b128 v[248:251], v200 offset:53312
	s_waitcnt lgkmcnt(3)
	v_mfma_f32_16x16x32_bf16 v[68:71], v[128:131], v[252:255], v[68:71]
	v_mfma_f32_16x16x32_bf16 v[12:15], v[132:135], v[252:255], v[12:15]
	ds_read_b128 v[252:255], v201 offset:53312
	s_waitcnt lgkmcnt(3)
	v_mfma_f32_16x16x32_bf16 v[72:75], v[128:131], v[136:139], v[72:75]
	v_mfma_f32_16x16x32_bf16 v[16:19], v[132:135], v[136:139], v[16:19]
	s_waitcnt lgkmcnt(2)
	v_mfma_f32_16x16x32_bf16 v[80:83], v[128:131], v[244:247], v[80:83]
	v_mfma_f32_16x16x32_bf16 v[20:23], v[132:135], v[244:247], v[20:23]
	s_waitcnt lgkmcnt(1)
	v_mfma_f32_16x16x32_bf16 v[104:107], v[128:131], v[248:251], v[104:107]
	v_mfma_f32_16x16x32_bf16 v[24:27], v[132:135], v[248:251], v[24:27]
	s_waitcnt lgkmcnt(0)
	v_mfma_f32_16x16x32_bf16 v[124:127], v[128:131], v[252:255], v[124:127]
	v_mfma_f32_16x16x32_bf16 v[92:95], v[132:135], v[252:255], v[92:95]
.LBB0_551:
	s_waitcnt lgkmcnt(0)
	s_andn2_b64 vcc, exec, s[4:5]
	s_cbranch_vccnz .LBB0_538
	s_cmp_gt_i32 s62, s57
	s_cbranch_scc1 .Latt_w0b
	s_waitcnt vmcnt(4)
	s_branch .Latt_wdb

; #define LAS __attribute__((address_space(3)))
; #define ATT_STORE(bi, kr, vr) do { LAS unsigned char* _k = lds + (bi) * 17408; LAS unsigned char* _v = lds + 34816 + (bi) * 18432; \
;         *(LAS u32x4*)(_k + kkey0 * 272 + kseg * 16) = kr[0]; *(LAS u32x4*)(_k + (kkey0 + 32) * 272 + kseg * 16) = kr[1]; \
;         *(LAS u32x4*)(_v + vdim0 * 144 + vseg * 16) = vr[0]; *(LAS u32x4*)(_v + (vdim0 + 64) * 144 + vseg * 16) = vr[1]; } while (0)
; __device__ __forceinline__ void attn_item(const Params& P, int item, LAS unsigned char* lds, float mfix2) {
;     ...
;           if (i + 1 < ntiles) ATT_STORE(0, krB, vrB);
;           __syncthreads(); }
; __device__ __forceinline__ void gla_scan_item(const Params& P, int item, LAS unsigned char* lds) {
;     const int tid = threadIdx.x, lane = tid & 63, wave = __builtin_amdgcn_readfirstlane(tid >> 6), r16 = lane & 15, q4 = lane >> 4;
;     const int es = item & 3, h = (item >> 2) & 3, b = (item >> 4) & 7, dir = item >> 7;
;     const int ch = (dir * 8 + b) * 4 + h;
;     const bf16_t* QE = (const bf16_t*)(P.ws + WS_QE); const bf16_t* KE = (const bf16_t*)(P.ws + WS_KE); const bf16_t* KDT = (const bf16_t*)(P.ws + WS_KDT);
;     const float* DEC = (const float*)(P.ws + WS_DEC); const bf16_t* VT = (const bf16_t*)(P.ws + WS_VT) + ((size_t)((b * 4 + h) * 256 + es * 64)) * KVLEN;
;     float* od = (float*)(P.ws + WS_X) + (size_t)dir * NTOK * 1024;
;     LAS unsigned char* Al = lds;
;     LAS unsigned char* ST0 = lds + 9216; LAS unsigned char* ST1 = ST0 + 17408;
;     LAS unsigned char* Lq = lds + 44032;
;     LAS unsigned char* Lk = Lq + 17408;
;     LAS unsigned char* Ld = Lk + 17408;
;     LAS unsigned char* Lv = Ld + 18432;
;     for (int i = tid; i < 17408 / 4; i += 512) ((LAS unsigned*)ST0)[i] = 0u;
;     f32x4 sreg[4];
; #pragma unroll
;     for (int eb = 0; eb < 4; ++eb) sreg[eb] = (f32x4){0.f, 0.f, 0.f, 0.f};
;     const int cbk = wave >> 1, hb = (wave & 1) * 2;
;     const int qrow = tid >> 4, qseg = tid & 15, drow = tid >> 3, dseg = tid & 7;
;     u32x4 rq[2], rk[2], rd[2], rv; f32x4 decn;
.Latt_wdb:
	ds_write_b128 v203, v[108:111]
	ds_write_b128 v203, v[112:115] offset:8704
	ds_write_b128 v204, v[120:123] offset:34816
	ds_write_b128 v204, v[116:119] offset:44032
	s_branch .LBB0_538
.LBB0_553:
	s_cmp_eq_u32 s82, 2
	s_cbranch_scc1 .LBB0_571
	v_and_b32_e32 v181, 7, v224
	s_cmpk_gt_i32 s22, 0xff
	s_cbranch_scc1 .Lp4_gla_end
	v_lshrrev_b32_e32 v5, 3, v224
	v_mul_u32_u24_e32 v6, 0x900, v5
	v_mov_b32_e32 v55, 0
	v_lshlrev_b32_e32 v54, 1, v6
	v_lshl_add_u64 v[6:7], s[50:51], 0, v[54:55]
	s_mov_b64 s[0:1], 0x2bd18000
	v_lshl_add_u64 v[56:57], v[6:7], 0, s[0:1]
	v_lshlrev_b32_e32 v6, 4, v181
	v_mov_b32_e32 v7, v55
	s_add_u32 s44, s50, 0x2e118000
	v_lshl_add_u64 v[8:9], s[50:51], 0, v[6:7]
	s_mov_b64 s[0:1], 0x15818000
	s_addc_u32 s45, s51, 0
	v_lshl_add_u64 v[60:61], v[8:9], 0, s[0:1]
	s_add_i32 s0, 0, 0x13400
	s_add_i32 s1, 0, 0x17c00
	s_waitcnt lgkmcnt(0)
	v_bfe_u32 v3, v224, 4, 2
	v_and_b32_e32 v52, 15, v224
	s_movk_i32 s20, 0x90
	v_mov_b32_e32 v7, s0
	v_mov_b32_e32 v8, s1
	v_lshrrev_b32_e32 v1, 4, v224
	v_lshlrev_b32_e32 v2, 6, v5
	v_mad_u32_u24 v7, v5, s20, v7
	v_mad_u32_u24 v5, v5, s20, v8
	v_lshlrev_b32_e32 v62, 4, v3
	v_lshlrev_b32_e32 v8, 4, v52
	v_mov_b32_e32 v9, v55
	v_sub_u32_e32 v17, 0x10ff, v224
	v_add_u32_e32 v4, 0x1000, v2
	v_mov_b32_e32 v63, v55
	v_add_u32_e32 v59, s0, v62
	v_lshl_add_u64 v[10:11], s[50:51], 0, v[8:9]
	s_movk_i32 s21, 0x110
	s_add_i32 s0, 0, 0xf000
	v_lshrrev_b32_e32 v66, 9, v17
	v_lshlrev_b32_e32 v54, 8, v1
	v_lshlrev_b32_e32 v0, 3, v181
	v_lshlrev_b32_e32 v58, 2, v3
	s_mov_b32 s57, 0
	v_add_u32_e32 v14, 0x2400, v7
	v_lshl_add_u64 v[64:65], s[44:45], 0, v[62:63]
	v_add_u32_e32 v63, s1, v62
	v_lshl_add_u64 v[12:13], s[34:35], 0, v[8:9]
	v_mul_u32_u24_e32 v3, 0x110, v1
	v_add_u32_e32 v9, s0, v8
	v_mad_u32_u24 v15, v1, s21, 0
	v_mul_u32_u24_e32 v16, 0x90, v52
	v_add_u32_e32 v17, 2, v66
	v_lshl_add_u64 v[10:11], v[10:11], 0, v[54:55]
	s_mov_b64 s[0:1], 0x29918000
	v_lshl_add_u32 v1, v224, 2, 0
	v_lshlrev_b32_e32 v74, 1, v4
	s_mov_b32 s55, 1
	v_add_u32_e32 v67, 0, v62
	s_waitcnt vmcnt(11)
	v_or_b32_e32 v86, 0xffffff00, v58
	v_mul_u32_u24_e32 v87, 0x110, v52
	s_waitcnt vmcnt(8)
	v_and_b32_e32 v88, 30, v17
	v_mov_b32_e32 v53, v66
	v_or_b32_e32 v89, 16, v52
	v_lshl_add_u64 v[68:69], v[10:11], 0, s[0:1]
	v_lshl_add_u64 v[70:71], v[12:13], 0, v[54:55]
	v_add_u32_e32 v90, 0x2400, v1
	s_mov_b32 s54, s57
	v_lshlrev_b32_e32 v91, 2, v58
	v_lshlrev_b32_e32 v72, 1, v0
	v_mov_b32_e32 v73, v55
	v_lshlrev_b32_e32 v54, 1, v2
	s_movk_i32 s28, 0x2000
	s_movk_i32 s29, 0x6800
	s_movk_i32 s30, 0x8c0
	v_mov_b32_e32 v76, v74
	v_mov_b32_e32 v77, v55
	v_add_u32_e32 v92, v7, v6
	v_add_u32_e32 v93, v14, v6
	v_add_u32_e32 v94, v5, v6
	v_lshlrev_b32_e32 v78, 2, v52
	v_mov_b32_e32 v79, v55
	v_add_u32_e32 v95, v63, v16
	v_add_u32_e32 v96, v15, v8
	v_add_u32_e32 v97, v9, v3
	s_mov_b32 s31, s22
	s_branch .LBB0_556

; __global__ void __launch_bounds__(512, 2) mega(Params P) {
;     ...
;         for (int it = blockIdx.x; it < 512; it += gridDim.x) attn_item(P, it, lds, mfix2);
;         for (int it = blockIdx.x; it < 256; it += gridDim.x) gla_scan_item(P, it, lds);
.Lp4_gla_end:
	s_cmp_lg_u32 s82, 1
	s_cbranch_scc1 .LBB0_571
	s_mov_b32 s82, 2
	s_branch .Lp4_att

; __global__ void __launch_bounds__(512, 2) mega(Params P) {
	.amdhsa_kernel _Z4mega6Params
		.amdhsa_group_segment_fixed_size 0
		.amdhsa_private_segment_fixed_size 0
		.amdhsa_kernarg_size 456
		.amdhsa_user_sgpr_count 2
		.amdhsa_user_sgpr_dispatch_ptr 0
		.amdhsa_user_sgpr_queue_ptr 0
		.amdhsa_user_sgpr_kernarg_segment_ptr 1
		.amdhsa_user_sgpr_dispatch_id 0
		.amdhsa_user_sgpr_kernarg_preload_length 0
		.amdhsa_user_sgpr_kernarg_preload_offset 0
		.amdhsa_user_sgpr_private_segment_size 0
		.amdhsa_uses_dynamic_stack 0
		.amdhsa_enable_private_segment 0
		.amdhsa_system_sgpr_workgroup_id_x 1
		.amdhsa_system_sgpr_workgroup_id_y 0
		.amdhsa_system_sgpr_workgroup_id_z 0
		.amdhsa_system_sgpr_workgroup_info 0
		.amdhsa_system_vgpr_workitem_id 2
		.amdhsa_next_free_vgpr 256
		.amdhsa_next_free_sgpr 102
		.amdhsa_accum_offset 256
		.amdhsa_reserve_vcc 1
		.amdhsa_float_round_mode_32 0
		.amdhsa_float_round_mode_16_64 0
		.amdhsa_float_denorm_mode_32 3
		.amdhsa_float_denorm_mode_16_64 3
		.amdhsa_dx10_clamp 1
		.amdhsa_ieee_mode 1
		.amdhsa_fp16_overflow 0
		.amdhsa_tg_split 0
		.amdhsa_exception_fp_ieee_invalid_op 0
		.amdhsa_exception_fp_denorm_src 0
		.amdhsa_exception_fp_ieee_div_zero 0
		.amdhsa_exception_fp_ieee_overflow 0
		.amdhsa_exception_fp_ieee_underflow 0
		.amdhsa_exception_fp_ieee_inexact 0
		.amdhsa_exception_int_div_zero 0
	.end_amdhsa_kernel

; __global__ void __launch_bounds__(512, 2) mega(Params P) {
amdhsa.kernels:
  - .agpr_count:     0
    .args:
      - .offset:         0
        .size:           200
        .value_kind:     by_value
      - .offset:         200
        .size:           4
        .value_kind:     hidden_block_count_x
      - .offset:         204
        .size:           4
        .value_kind:     hidden_block_count_y
      - .offset:         208
        .size:           4
        .value_kind:     hidden_block_count_z
      - .offset:         212
        .size:           2
        .value_kind:     hidden_group_size_x
      - .offset:         214
        .size:           2
        .value_kind:     hidden_group_size_y
      - .offset:         216
        .size:           2
        .value_kind:     hidden_group_size_z
      - .offset:         218
        .size:           2
        .value_kind:     hidden_remainder_x
      - .offset:         220
        .size:           2
        .value_kind:     hidden_remainder_y
      - .offset:         222
        .size:           2
        .value_kind:     hidden_remainder_z
      - .offset:         240
        .size:           8
        .value_kind:     hidden_global_offset_x
      - .offset:         248
        .size:           8
        .value_kind:     hidden_global_offset_y
      - .offset:         256
        .size:           8
        .value_kind:     hidden_global_offset_z
      - .offset:         264
        .size:           2
        .value_kind:     hidden_grid_dims
      - .offset:         288
        .size:           8
        .value_kind:     hidden_multigrid_sync_arg
      - .offset:         320
        .size:           4
        .value_kind:     hidden_dynamic_lds_size
    .group_segment_fixed_size: 0
    .kernarg_segment_align: 8
    .kernarg_segment_size: 456
    .language:       OpenCL C
    .language_version:
      - 2
      - 0
    .max_flat_workgroup_size: 512
    .name:           _Z4mega6Params
    .private_segment_fixed_size: 0
    .sgpr_count:     108
    .sgpr_spill_count: 6
    .symbol:         _Z4mega6Params.kd
    .uniform_work_group_size: 1
    .uses_dynamic_stack: false
    .vgpr_count:     256
    .vgpr_spill_count: 0
    .wavefront_size: 64
